# in-proj epilogue rope: the 16 serialized rope-table load groups per unit replaced by one staged copy in 24 KB of static LDS (8 loads per wave per unit) + ds_read_b128; removes the per-block vmcnt(0) s
# baseline (speedup 1.0000x reference)
;     __device__ __forceinline__ void operator()(AccRef acc, const pg8::Unit& u, int wr, int wc, int, int) const {
;     ...
; #pragma unroll
;         for (int ai = 0; ai < 2; ++ai)
; #pragma unroll
;             for (int m = 0; m < 4; ++m) sq[ai][m] = ssq[pm * 256 + ai * 128 + wr * 64 + m * 16 + fr];
;         asm volatile("" ::: "memory");
; #pragma unroll
;         for (int ai = 0; ai < 2; ++ai)
; #pragma unroll
;             for (int m = 0; m < 4; ++m) {
;                 const int row = pm * 256 + ai * 128 + wr * 64 + m * 16 + fr;
;                 const float rstd = __builtin_amdgcn_rsqf(sq[ai][m] * (1.0f / DM) + EPS) * (isq ? QSCALE : 1.0f);
;                 const int pos = samp ? 2048 + ((row - MP) & 63) : (row & 16383);
; #pragma unroll
;                 for (int bj = 0; bj < 2; ++bj) {
;                     const int c0 = pn * 256 + bj * 128 + wc * 32 + 8 * fq;
;                     float v[8];
; #pragma unroll
;                     for (int j = 0; j < 4; ++j) { v[j] = acc[ai][bj][m][0][j] * rstd; v[4 + j] = acc[ai][bj][m][1][j] * rstd; }
;                     const bool ropet = (pn == 6 || pn == 7 || (pn == 8 && bj == 0)) && ((wc & 1) == 0);
;                     if (ropet) {
;                         float pv[8];
; #pragma unroll
;                         for (int j = 0; j < 8; ++j) pv[j] = __shfl_xor(v[j], 16);
;                         if (fq < 2) {
;                             const f32x4* cs = (const f32x4*)(rope + (size_t)pos * 16);
;                             const float sg = (fq == 0) ? -1.f : 1.f;
; #pragma unroll
;                             for (int jj = 0; jj < 4; ++jj) { const f32x4 t = cs[jj];
;                                 v[2 * jj] = v[2 * jj] * t[0] + sg * pv[2 * jj] * t[1];
;                                 v[2 * jj + 1] = v[2 * jj + 1] * t[2] + sg * pv[2 * jj + 1] * t[3]; }
;                         }
.LBB0_158:
	s_mov_b64 s[8:9], s[44:45]
	s_mov_b64 s[94:95], s[46:47]
	s_add_u32 s6, s8, 0x1000
	s_addc_u32 s7, s9, 0
	s_cmpk_gt_i32 s84, 0x7f
	s_cselect_b64 s[4:5], -1, 0
	s_cmp_lt_i32 s12, 2
	s_cselect_b64 s[10:11], -1, 0
	s_and_b32 s13, s12, -2
	s_cmp_eq_u32 s13, 6
	v_mov_b32_e32 v136, v196
	s_cselect_b64 s[56:57], -1, 0
	s_lshl_b32 s53, s84, 8
	s_add_i32 s53, s53, s35
	v_and_b32_e32 v177, 15, v136
	v_or_b32_e32 v144, s53, v177
	v_ashrrev_i32_e32 v145, 31, v144
	v_or_b32_e32 v154, 16, v144
	v_lshl_add_u64 v[146:147], v[144:145], 2, s[6:7]
	v_ashrrev_i32_e32 v155, 31, v154
	v_or_b32_e32 v152, 32, v144
	global_load_dword v148, v[146:147], off
	v_lshl_add_u64 v[146:147], v[154:155], 2, s[6:7]
	v_ashrrev_i32_e32 v153, 31, v152
	v_or_b32_e32 v150, 48, v144
	global_load_dword v182, v[146:147], off
	v_lshl_add_u64 v[146:147], v[152:153], 2, s[6:7]
	v_ashrrev_i32_e32 v151, 31, v150
	global_load_dword v181, v[146:147], off
	v_lshl_add_u64 v[146:147], v[150:151], 2, s[6:7]
	global_load_dword v180, v[146:147], off
	v_add_u32_e32 v146, 0x80, v144
	v_ashrrev_i32_e32 v147, 31, v146
	v_lshl_add_u64 v[146:147], v[146:147], 2, s[6:7]
	global_load_dword v178, v[146:147], off
	v_add_u32_e32 v146, 0x90, v144
	v_ashrrev_i32_e32 v147, 31, v146
	v_lshl_add_u64 v[146:147], v[146:147], 2, s[6:7]
	global_load_dword v176, v[146:147], off
	v_add_u32_e32 v146, 0xa0, v144
	v_ashrrev_i32_e32 v147, 31, v146
	v_lshl_add_u64 v[146:147], v[146:147], 2, s[6:7]
	global_load_dword v155, v[146:147], off
	v_add_u32_e32 v146, 0xb0, v144
	v_ashrrev_i32_e32 v147, 31, v146
	v_lshl_add_u64 v[146:147], v[146:147], 2, s[6:7]
	global_load_dword v153, v[146:147], off
	s_or_b64 vcc, s[10:11], s[56:57]
	v_ashrrev_i32_e32 v145, 4, v136
	v_cndmask_b32_e32 v151, 1.0, v175, vcc
	v_cmp_gt_u32_e32 vcc, 16, v136
	s_add_u32 s96, s8, 0x100000
	s_addc_u32 s97, s9, 0
	s_add_i32 s10, s12, -6
	v_or_b32_e32 v179, 0x800, v177
	s_cmp_lt_u32 s10, 3
	s_cselect_b64 s[10:11], -1, 0
	s_and_b64 s[14:15], s[78:79], s[10:11]
	v_cmp_gt_i32_e64 s[6:7], 2, v145
	v_cndmask_b32_e64 v142, 1.0, -1.0, vcc
	s_andn2_b64 vcc, exec, s[14:15]
	s_waitcnt vmcnt(0)
	v_fmamk_f32 v136, v148, 0x3a800000, v174
	v_rsq_f32_e32 v136, v136
	s_nop 0
	v_mul_f32_e32 v156, v151, v136
	v_mov_b32_e32 v136, s53
	v_bitop3_b32 v157, v177, s70, v136 bitop3:0xc8
	v_cndmask_b32_e64 v136, v157, v179, s[4:5]
	v_lshlrev_b32_e32 v136, 6, v136
	v_lshl_add_u64 v[158:159], s[96:97], 0, v[136:137]
	v_cndmask_b32_e64 v136, 0, 1, s[14:15]
	v_pk_mul_f32 v[124:125], v[124:125], v[156:157] op_sel_hi:[1,0]
	v_pk_mul_f32 v[120:121], v[120:121], v[156:157] op_sel_hi:[1,0]
	v_pk_mul_f32 v[126:127], v[126:127], v[156:157] op_sel_hi:[1,0]
	v_pk_mul_f32 v[122:123], v[122:123], v[156:157] op_sel_hi:[1,0]
	v_cmp_ne_u32_e64 s[10:11], 1, v136
	s_cbranch_vccnz .LBB0_162
	v_readfirstlane_b32 s30, v158
	v_readfirstlane_b32 s31, v159
	v_mbcnt_lo_u32_b32 v236, -1, 0
	v_mbcnt_hi_u32_b32 v236, -1, v236
	v_lshlrev_b32_e32 v236, 4, v236
	s_nop 4
	s_sub_u32 s32, s30, s96
	s_bfe_u32 s32, s32, 0x1000c
	s_mul_i32 s32, s32, 0x3000
	s_add_i32 s32, s32, 0x21000
	s_add_u32 s36, s30, 0x2000
	s_addc_u32 s37, s31, 0
	global_load_dwordx4 v[204:207], v236, s[30:31]
	global_load_dwordx4 v[208:211], v236, s[30:31] offset:1024
	global_load_dwordx4 v[212:215], v236, s[30:31] offset:2048
	global_load_dwordx4 v[216:219], v236, s[30:31] offset:3072
	global_load_dwordx4 v[220:223], v236, s[36:37]
	global_load_dwordx4 v[224:227], v236, s[36:37] offset:1024
	global_load_dwordx4 v[228:231], v236, s[36:37] offset:2048
	global_load_dwordx4 v[232:235], v236, s[36:37] offset:3072
	v_add_u32_e32 v237, s32, v236
	s_sub_u32 s32, s30, s32
	s_waitcnt vmcnt(0)
	ds_write_b128 v237, v[204:207]
	ds_write_b128 v237, v[208:211] offset:1024
	ds_write_b128 v237, v[212:215] offset:2048
	ds_write_b128 v237, v[216:219] offset:3072
	ds_write_b128 v237, v[220:223] offset:8192
	ds_write_b128 v237, v[224:227] offset:9216
	ds_write_b128 v237, v[228:231] offset:10240
	ds_write_b128 v237, v[232:235] offset:11264
	s_waitcnt lgkmcnt(0)
	ds_bpermute_b32 v160, v168, v124
	ds_bpermute_b32 v161, v168, v125
	ds_bpermute_b32 v148, v168, v126
	ds_bpermute_b32 v149, v168, v127
	ds_bpermute_b32 v146, v168, v120
	ds_bpermute_b32 v147, v168, v121
	ds_bpermute_b32 v162, v168, v122
	ds_bpermute_b32 v136, v168, v123
	s_and_saveexec_b64 s[14:15], s[6:7]
	s_cbranch_execz .LBB0_161
	v_subrev_u32_e32 v240, s32, v158
	ds_read_b128 v[184:187], v240 offset:48
	ds_read_b128 v[188:191], v240 offset:32
	ds_read_b128 v[192:195], v240 offset:16
	ds_read_b128 v[198:201], v240
	s_waitcnt lgkmcnt(1)
	v_mul_f32_e32 v162, v142, v162
	v_pk_mul_f32 v[160:161], v[142:143], v[160:161] op_sel_hi:[0,1]
	v_pk_mul_f32 v[148:149], v[142:143], v[148:149] op_sel_hi:[0,1]
	v_pk_mul_f32 v[146:147], v[142:143], v[146:147] op_sel_hi:[0,1]
	s_waitcnt lgkmcnt(0)
	v_mul_f32_e32 v122, v122, v184
	v_mul_f32_e32 v162, v162, v185
	v_mov_b32_e32 v164, v198
	v_mov_b32_e32 v165, v200
	v_pk_mul_f32 v[124:125], v[124:125], v[164:165]
	v_mov_b32_e32 v164, v192
	v_mov_b32_e32 v165, v194
	v_pk_mul_f32 v[126:127], v[126:127], v[164:165]
	v_mov_b32_e32 v164, v188
	v_mov_b32_e32 v165, v190
	v_pk_mul_f32 v[120:121], v[120:121], v[164:165]
	s_waitcnt lgkmcnt(0)
	v_mul_f32_e32 v165, v142, v136
	v_mov_b32_e32 v164, v123
	v_pk_mul_f32 v[164:165], v[164:165], v[186:187]
	v_mov_b32_e32 v200, v199
	v_mov_b32_e32 v194, v193
	v_mov_b32_e32 v190, v189
	v_mov_b32_e32 v123, v165
	v_mov_b32_e32 v163, v164
	v_pk_fma_f32 v[124:125], v[160:161], v[200:201], v[124:125]
	v_pk_fma_f32 v[126:127], v[148:149], v[194:195], v[126:127]
	v_pk_fma_f32 v[120:121], v[146:147], v[190:191], v[120:121]
	v_pk_add_f32 v[122:123], v[122:123], v[162:163]

;     __device__ __forceinline__ void operator()(AccRef acc, const pg8::Unit& u, int wr, int wc, int, int) const {
;     ...
;                 for (int bj = 0; bj < 2; ++bj) {
;                     const int c0 = pn * 256 + bj * 128 + wc * 32 + 8 * fq;
;                     float v[8];
; #pragma unroll
;                     for (int j = 0; j < 4; ++j) { v[j] = acc[ai][bj][m][0][j] * rstd; v[4 + j] = acc[ai][bj][m][1][j] * rstd; }
;                     const bool ropet = (pn == 6 || pn == 7 || (pn == 8 && bj == 0)) && ((wc & 1) == 0);
;                     if (ropet) {
;                         float pv[8];
; #pragma unroll
;                         for (int j = 0; j < 8; ++j) pv[j] = __shfl_xor(v[j], 16);
;                         if (fq < 2) {
;                             const f32x4* cs = (const f32x4*)(rope + (size_t)pos * 16);
;                             const float sg = (fq == 0) ? -1.f : 1.f;
; #pragma unroll
;                             for (int jj = 0; jj < 4; ++jj) { const f32x4 t = cs[jj];
;                                 v[2 * jj] = v[2 * jj] * t[0] + sg * pv[2 * jj] * t[1];
;                                 v[2 * jj + 1] = v[2 * jj + 1] * t[2] + sg * pv[2 * jj + 1] * t[3]; }
;                         }
.LBB0_166:
	s_and_b64 s[48:49], s[78:79], s[56:57]
	v_mov_b32_e32 v157, v156
	v_cndmask_b32_e64 v120, 0, 1, s[48:49]
	v_pk_mul_f32 v[116:117], v[116:117], v[156:157]
	v_pk_mul_f32 v[112:113], v[112:113], v[156:157]
	v_pk_mul_f32 v[118:119], v[118:119], v[156:157]
	v_cmp_ne_u32_e64 s[12:13], 1, v120
	s_andn2_b64 vcc, exec, s[48:49]
	v_pk_mul_f32 v[114:115], v[114:115], v[156:157]
	s_cbranch_vccnz .LBB0_170
	ds_bpermute_b32 v124, v168, v116
	ds_bpermute_b32 v125, v168, v117
	ds_bpermute_b32 v122, v168, v118
	ds_bpermute_b32 v123, v168, v119
	ds_bpermute_b32 v120, v168, v112
	ds_bpermute_b32 v121, v168, v113
	ds_bpermute_b32 v127, v168, v114
	ds_bpermute_b32 v126, v168, v115
	s_and_saveexec_b64 s[56:57], s[6:7]
	s_cbranch_execz .LBB0_169
	v_subrev_u32_e32 v240, s32, v158
	ds_read_b128 v[184:187], v240 offset:48
	ds_read_b128 v[188:191], v240 offset:32
	ds_read_b128 v[192:195], v240 offset:16
	s_nop 0
	ds_read_b128 v[156:159], v240
	s_waitcnt lgkmcnt(1)
	v_mul_f32_e32 v127, v142, v127
	v_pk_mul_f32 v[124:125], v[142:143], v[124:125] op_sel_hi:[0,1]
	v_pk_mul_f32 v[122:123], v[142:143], v[122:123] op_sel_hi:[0,1]
	v_pk_mul_f32 v[120:121], v[142:143], v[120:121] op_sel_hi:[0,1]
	s_waitcnt lgkmcnt(0)
	v_mul_f32_e32 v114, v114, v184
	v_mov_b32_e32 v198, v156
	v_mov_b32_e32 v199, v158
	v_mov_b32_e32 v158, v157
	v_mov_b32_e32 v156, v192
	v_mov_b32_e32 v157, v194
	v_pk_mul_f32 v[118:119], v[118:119], v[156:157]
	v_mov_b32_e32 v156, v188
	v_mov_b32_e32 v157, v190
	v_pk_mul_f32 v[112:113], v[112:113], v[156:157]
	v_mul_f32_e32 v156, v127, v185
	s_waitcnt lgkmcnt(0)
	v_mul_f32_e32 v127, v142, v126
	v_mov_b32_e32 v126, v115
	v_pk_mul_f32 v[126:127], v[126:127], v[186:187]
	v_pk_mul_f32 v[116:117], v[116:117], v[198:199]
	v_mov_b32_e32 v194, v193
	v_mov_b32_e32 v190, v189
	v_mov_b32_e32 v115, v127
	v_mov_b32_e32 v157, v126
	v_pk_fma_f32 v[116:117], v[124:125], v[158:159], v[116:117]
	v_pk_fma_f32 v[118:119], v[122:123], v[194:195], v[118:119]
	v_pk_fma_f32 v[112:113], v[120:121], v[190:191], v[112:113]
	v_pk_add_f32 v[114:115], v[114:115], v[156:157]

;     __device__ __forceinline__ void operator()(AccRef acc, const pg8::Unit& u, int wr, int wc, int, int) const {
;     ...
;                 const int row = pm * 256 + ai * 128 + wr * 64 + m * 16 + fr;
;                 const float rstd = __builtin_amdgcn_rsqf(sq[ai][m] * (1.0f / DM) + EPS) * (isq ? QSCALE : 1.0f);
;                 const int pos = samp ? 2048 + ((row - MP) & 63) : (row & 16383);
; #pragma unroll
;                 for (int bj = 0; bj < 2; ++bj) {
;                     const int c0 = pn * 256 + bj * 128 + wc * 32 + 8 * fq;
;                     float v[8];
; #pragma unroll
;                     for (int j = 0; j < 4; ++j) { v[j] = acc[ai][bj][m][0][j] * rstd; v[4 + j] = acc[ai][bj][m][1][j] * rstd; }
;                     const bool ropet = (pn == 6 || pn == 7 || (pn == 8 && bj == 0)) && ((wc & 1) == 0);
;                     if (ropet) {
;                         float pv[8];
; #pragma unroll
;                         for (int j = 0; j < 8; ++j) pv[j] = __shfl_xor(v[j], 16);
;                         if (fq < 2) {
;                             const f32x4* cs = (const f32x4*)(rope + (size_t)pos * 16);
;                             const float sg = (fq == 0) ? -1.f : 1.f;
; #pragma unroll
;                             for (int jj = 0; jj < 4; ++jj) { const f32x4 t = cs[jj];
;                                 v[2 * jj] = v[2 * jj] * t[0] + sg * pv[2 * jj] * t[1];
;                                 v[2 * jj + 1] = v[2 * jj + 1] * t[2] + sg * pv[2 * jj + 1] * t[3]; }
;                         }
.LBB0_174:
	s_nop 1
	v_fmamk_f32 v112, v182, 0x3a800000, v174
	v_rsq_f32_e32 v112, v112
	v_or_b32_e32 v125, 0x810, v177
	v_and_b32_e32 v115, 0x3fdf, v154
	v_cndmask_b32_e64 v113, v115, v125, s[4:5]
	v_mul_f32_e32 v114, v151, v112
	v_lshlrev_b32_e32 v136, 6, v113
	v_lshl_add_u64 v[112:113], s[96:97], 0, v[136:137]
	v_pk_mul_f32 v[108:109], v[108:109], v[114:115] op_sel_hi:[1,0]
	v_pk_mul_f32 v[104:105], v[104:105], v[114:115] op_sel_hi:[1,0]
	v_pk_mul_f32 v[110:111], v[110:111], v[114:115] op_sel_hi:[1,0]
	s_and_b64 vcc, exec, s[10:11]
	v_pk_mul_f32 v[106:107], v[106:107], v[114:115] op_sel_hi:[1,0]
	s_cbranch_vccnz .LBB0_178
	ds_bpermute_b32 v122, v168, v108
	ds_bpermute_b32 v123, v168, v109
	ds_bpermute_b32 v118, v168, v110
	ds_bpermute_b32 v119, v168, v111
	ds_bpermute_b32 v116, v168, v104
	ds_bpermute_b32 v117, v168, v105
	s_waitcnt lgkmcnt(6)
	ds_bpermute_b32 v126, v168, v106
	ds_bpermute_b32 v124, v168, v107
	s_and_saveexec_b64 s[56:57], s[6:7]
	s_cbranch_execz .LBB0_177
	v_subrev_u32_e32 v240, s32, v112
	ds_read_b128 v[156:159], v240 offset:48
	ds_read_b128 v[160:163], v240 offset:32
	ds_read_b128 v[182:185], v240 offset:16
	ds_read_b128 v[186:189], v240
	s_waitcnt lgkmcnt(1)
	v_mul_f32_e32 v126, v142, v126
	v_pk_mul_f32 v[122:123], v[142:143], v[122:123] op_sel_hi:[0,1]
	v_pk_mul_f32 v[118:119], v[142:143], v[118:119] op_sel_hi:[0,1]
	v_pk_mul_f32 v[116:117], v[142:143], v[116:117] op_sel_hi:[0,1]
	s_waitcnt lgkmcnt(0)
	v_mul_f32_e32 v106, v106, v156
	v_mul_f32_e32 v126, v126, v157
	s_waitcnt lgkmcnt(0)
	v_mul_f32_e32 v157, v142, v124
	v_mov_b32_e32 v164, v186
	v_mov_b32_e32 v165, v188
	v_pk_mul_f32 v[108:109], v[108:109], v[164:165]
	v_mov_b32_e32 v164, v182
	v_mov_b32_e32 v165, v184
	v_mov_b32_e32 v156, v107
	v_pk_mul_f32 v[110:111], v[110:111], v[164:165]
	v_mov_b32_e32 v164, v160
	v_mov_b32_e32 v165, v162
	v_pk_mul_f32 v[156:157], v[156:157], v[158:159]
	v_mov_b32_e32 v188, v187
	v_mov_b32_e32 v184, v183
	v_pk_mul_f32 v[104:105], v[104:105], v[164:165]
	v_mov_b32_e32 v162, v161
	v_mov_b32_e32 v107, v157
	v_mov_b32_e32 v127, v156
	v_pk_fma_f32 v[108:109], v[122:123], v[188:189], v[108:109]
	v_pk_fma_f32 v[110:111], v[118:119], v[184:185], v[110:111]
	v_pk_fma_f32 v[104:105], v[116:117], v[162:163], v[104:105]
	v_pk_add_f32 v[106:107], v[106:107], v[126:127]

;     __device__ __forceinline__ void operator()(AccRef acc, const pg8::Unit& u, int wr, int wc, int, int) const {
;     ...
;                 const int row = pm * 256 + ai * 128 + wr * 64 + m * 16 + fr;
;                 const float rstd = __builtin_amdgcn_rsqf(sq[ai][m] * (1.0f / DM) + EPS) * (isq ? QSCALE : 1.0f);
;                 const int pos = samp ? 2048 + ((row - MP) & 63) : (row & 16383);
; #pragma unroll
;                 for (int bj = 0; bj < 2; ++bj) {
;                     const int c0 = pn * 256 + bj * 128 + wc * 32 + 8 * fq;
;                     float v[8];
; #pragma unroll
;                     for (int j = 0; j < 4; ++j) { v[j] = acc[ai][bj][m][0][j] * rstd; v[4 + j] = acc[ai][bj][m][1][j] * rstd; }
;                     const bool ropet = (pn == 6 || pn == 7 || (pn == 8 && bj == 0)) && ((wc & 1) == 0);
;                     if (ropet) {
;                         float pv[8];
; #pragma unroll
;                         for (int j = 0; j < 8; ++j) pv[j] = __shfl_xor(v[j], 16);
;                         if (fq < 2) {
;                             const f32x4* cs = (const f32x4*)(rope + (size_t)pos * 16);
;                             const float sg = (fq == 0) ? -1.f : 1.f;
; #pragma unroll
;                             for (int jj = 0; jj < 4; ++jj) { const f32x4 t = cs[jj];
;                                 v[2 * jj] = v[2 * jj] * t[0] + sg * pv[2 * jj] * t[1];
;                                 v[2 * jj + 1] = v[2 * jj + 1] * t[2] + sg * pv[2 * jj + 1] * t[3]; }
;                         }
.LBB0_182:
	v_mov_b32_e32 v115, v114
	v_pk_mul_f32 v[100:101], v[100:101], v[114:115]
	v_pk_mul_f32 v[96:97], v[96:97], v[114:115]
	v_pk_mul_f32 v[102:103], v[102:103], v[114:115]
	s_and_b64 vcc, exec, s[12:13]
	v_pk_mul_f32 v[98:99], v[98:99], v[114:115]
	s_cbranch_vccnz .LBB0_186
	ds_bpermute_b32 v108, v168, v100
	ds_bpermute_b32 v109, v168, v101
	ds_bpermute_b32 v106, v168, v102
	ds_bpermute_b32 v107, v168, v103
	ds_bpermute_b32 v104, v168, v96
	ds_bpermute_b32 v105, v168, v97
	ds_bpermute_b32 v111, v168, v98
	ds_bpermute_b32 v110, v168, v99
	s_and_saveexec_b64 s[56:57], s[6:7]
	s_cbranch_execz .LBB0_185
	v_subrev_u32_e32 v240, s32, v112
	ds_read_b128 v[156:159], v240 offset:48
	ds_read_b128 v[160:163], v240 offset:32
	ds_read_b128 v[182:185], v240 offset:16
	s_nop 0
	ds_read_b128 v[112:115], v240
	s_waitcnt lgkmcnt(1)
	v_mul_f32_e32 v111, v142, v111
	v_pk_mul_f32 v[108:109], v[142:143], v[108:109] op_sel_hi:[0,1]
	v_pk_mul_f32 v[106:107], v[142:143], v[106:107] op_sel_hi:[0,1]
	v_pk_mul_f32 v[104:105], v[142:143], v[104:105] op_sel_hi:[0,1]
	s_waitcnt lgkmcnt(0)
	v_mul_f32_e32 v98, v98, v156
	v_mov_b32_e32 v126, v112
	v_mov_b32_e32 v127, v114
	v_mov_b32_e32 v114, v113
	v_mov_b32_e32 v112, v182
	v_mov_b32_e32 v113, v184
	v_pk_mul_f32 v[102:103], v[102:103], v[112:113]
	v_mov_b32_e32 v112, v160
	v_mov_b32_e32 v113, v162
	v_pk_mul_f32 v[96:97], v[96:97], v[112:113]
	v_mul_f32_e32 v112, v111, v157
	s_waitcnt lgkmcnt(0)
	v_mul_f32_e32 v111, v142, v110
	v_mov_b32_e32 v110, v99
	v_pk_mul_f32 v[110:111], v[110:111], v[158:159]
	v_pk_mul_f32 v[100:101], v[100:101], v[126:127]
	v_mov_b32_e32 v184, v183
	v_mov_b32_e32 v162, v161
	v_mov_b32_e32 v99, v111
	v_mov_b32_e32 v113, v110
	v_pk_fma_f32 v[100:101], v[108:109], v[114:115], v[100:101]
	v_pk_fma_f32 v[102:103], v[106:107], v[184:185], v[102:103]
	v_pk_fma_f32 v[96:97], v[104:105], v[162:163], v[96:97]
	v_pk_add_f32 v[98:99], v[98:99], v[112:113]

;     __device__ __forceinline__ void operator()(AccRef acc, const pg8::Unit& u, int wr, int wc, int, int) const {
;     ...
;                 const int row = pm * 256 + ai * 128 + wr * 64 + m * 16 + fr;
;                 const float rstd = __builtin_amdgcn_rsqf(sq[ai][m] * (1.0f / DM) + EPS) * (isq ? QSCALE : 1.0f);
;                 const int pos = samp ? 2048 + ((row - MP) & 63) : (row & 16383);
; #pragma unroll
;                 for (int bj = 0; bj < 2; ++bj) {
;                     const int c0 = pn * 256 + bj * 128 + wc * 32 + 8 * fq;
;                     float v[8];
; #pragma unroll
;                     for (int j = 0; j < 4; ++j) { v[j] = acc[ai][bj][m][0][j] * rstd; v[4 + j] = acc[ai][bj][m][1][j] * rstd; }
;                     const bool ropet = (pn == 6 || pn == 7 || (pn == 8 && bj == 0)) && ((wc & 1) == 0);
;                     if (ropet) {
;                         float pv[8];
; #pragma unroll
;                         for (int j = 0; j < 8; ++j) pv[j] = __shfl_xor(v[j], 16);
;                         if (fq < 2) {
;                             const f32x4* cs = (const f32x4*)(rope + (size_t)pos * 16);
;                             const float sg = (fq == 0) ? -1.f : 1.f;
; #pragma unroll
;                             for (int jj = 0; jj < 4; ++jj) { const f32x4 t = cs[jj];
;                                 v[2 * jj] = v[2 * jj] * t[0] + sg * pv[2 * jj] * t[1];
;                                 v[2 * jj + 1] = v[2 * jj + 1] * t[2] + sg * pv[2 * jj + 1] * t[3]; }
;                         }
.LBB0_190:
	s_nop 1
	v_fmamk_f32 v96, v181, 0x3a800000, v174
	v_rsq_f32_e32 v96, v96
	v_or_b32_e32 v107, 0x820, v177
	v_and_b32_e32 v99, 0x3fef, v152
	v_cndmask_b32_e64 v97, v99, v107, s[4:5]
	v_mul_f32_e32 v98, v151, v96
	v_lshlrev_b32_e32 v136, 6, v97
	v_lshl_add_u64 v[96:97], s[96:97], 0, v[136:137]
	v_pk_mul_f32 v[92:93], v[92:93], v[98:99] op_sel_hi:[1,0]
	v_pk_mul_f32 v[88:89], v[88:89], v[98:99] op_sel_hi:[1,0]
	v_pk_mul_f32 v[94:95], v[94:95], v[98:99] op_sel_hi:[1,0]
	s_and_b64 vcc, exec, s[10:11]
	v_pk_mul_f32 v[90:91], v[90:91], v[98:99] op_sel_hi:[1,0]
	s_cbranch_vccnz .LBB0_194
	ds_bpermute_b32 v104, v168, v92
	ds_bpermute_b32 v105, v168, v93
	ds_bpermute_b32 v102, v168, v94
	ds_bpermute_b32 v103, v168, v95
	ds_bpermute_b32 v100, v168, v88
	ds_bpermute_b32 v101, v168, v89
	ds_bpermute_b32 v108, v168, v90
	ds_bpermute_b32 v106, v168, v91
	s_and_saveexec_b64 s[56:57], s[6:7]
	s_cbranch_execz .LBB0_193
	s_waitcnt lgkmcnt(8)
	v_subrev_u32_e32 v240, s32, v96
	ds_read_b128 v[110:113], v240 offset:48
	ds_read_b128 v[114:117], v240 offset:32
	ds_read_b128 v[156:159], v240 offset:16
	ds_read_b128 v[160:163], v240
	s_waitcnt lgkmcnt(1)
	v_mul_f32_e32 v108, v142, v108
	v_pk_mul_f32 v[104:105], v[142:143], v[104:105] op_sel_hi:[0,1]
	v_pk_mul_f32 v[102:103], v[142:143], v[102:103] op_sel_hi:[0,1]
	v_pk_mul_f32 v[100:101], v[142:143], v[100:101] op_sel_hi:[0,1]
	s_waitcnt lgkmcnt(0)
	v_mul_f32_e32 v90, v90, v110
	v_mul_f32_e32 v108, v108, v111
	s_waitcnt lgkmcnt(0)
	v_mul_f32_e32 v111, v142, v106
	v_mov_b32_e32 v118, v160
	v_mov_b32_e32 v119, v162
	v_pk_mul_f32 v[92:93], v[92:93], v[118:119]
	v_mov_b32_e32 v118, v156
	v_mov_b32_e32 v119, v158
	v_mov_b32_e32 v110, v91
	v_pk_mul_f32 v[94:95], v[94:95], v[118:119]
	v_mov_b32_e32 v118, v114
	v_mov_b32_e32 v119, v116
	v_pk_mul_f32 v[110:111], v[110:111], v[112:113]
	v_mov_b32_e32 v162, v161
	v_mov_b32_e32 v158, v157
	v_pk_mul_f32 v[88:89], v[88:89], v[118:119]
	v_mov_b32_e32 v116, v115
	v_mov_b32_e32 v91, v111
	v_mov_b32_e32 v109, v110
	v_pk_fma_f32 v[92:93], v[104:105], v[162:163], v[92:93]
	v_pk_fma_f32 v[94:95], v[102:103], v[158:159], v[94:95]
	v_pk_fma_f32 v[88:89], v[100:101], v[116:117], v[88:89]
	v_pk_add_f32 v[90:91], v[90:91], v[108:109]

;     __device__ __forceinline__ void operator()(AccRef acc, const pg8::Unit& u, int wr, int wc, int, int) const {
;     ...
;                 const int row = pm * 256 + ai * 128 + wr * 64 + m * 16 + fr;
;                 const float rstd = __builtin_amdgcn_rsqf(sq[ai][m] * (1.0f / DM) + EPS) * (isq ? QSCALE : 1.0f);
;                 const int pos = samp ? 2048 + ((row - MP) & 63) : (row & 16383);
; #pragma unroll
;                 for (int bj = 0; bj < 2; ++bj) {
;                     const int c0 = pn * 256 + bj * 128 + wc * 32 + 8 * fq;
;                     float v[8];
; #pragma unroll
;                     for (int j = 0; j < 4; ++j) { v[j] = acc[ai][bj][m][0][j] * rstd; v[4 + j] = acc[ai][bj][m][1][j] * rstd; }
;                     const bool ropet = (pn == 6 || pn == 7 || (pn == 8 && bj == 0)) && ((wc & 1) == 0);
;                     if (ropet) {
;                         float pv[8];
; #pragma unroll
;                         for (int j = 0; j < 8; ++j) pv[j] = __shfl_xor(v[j], 16);
;                         if (fq < 2) {
;                             const f32x4* cs = (const f32x4*)(rope + (size_t)pos * 16);
;                             const float sg = (fq == 0) ? -1.f : 1.f;
; #pragma unroll
;                             for (int jj = 0; jj < 4; ++jj) { const f32x4 t = cs[jj];
;                                 v[2 * jj] = v[2 * jj] * t[0] + sg * pv[2 * jj] * t[1];
;                                 v[2 * jj + 1] = v[2 * jj + 1] * t[2] + sg * pv[2 * jj + 1] * t[3]; }
;                         }
.LBB0_198:
	v_mov_b32_e32 v99, v98
	v_pk_mul_f32 v[84:85], v[84:85], v[98:99]
	v_pk_mul_f32 v[80:81], v[80:81], v[98:99]
	v_pk_mul_f32 v[86:87], v[86:87], v[98:99]
	s_and_b64 vcc, exec, s[12:13]
	v_pk_mul_f32 v[82:83], v[82:83], v[98:99]
	s_cbranch_vccnz .LBB0_202
	ds_bpermute_b32 v92, v168, v84
	ds_bpermute_b32 v93, v168, v85
	ds_bpermute_b32 v90, v168, v86
	ds_bpermute_b32 v91, v168, v87
	ds_bpermute_b32 v88, v168, v80
	ds_bpermute_b32 v89, v168, v81
	ds_bpermute_b32 v95, v168, v82
	ds_bpermute_b32 v94, v168, v83
	s_and_saveexec_b64 s[56:57], s[6:7]
	s_cbranch_execz .LBB0_201
	v_subrev_u32_e32 v240, s32, v96
	ds_read_b128 v[108:111], v240 offset:48
	ds_read_b128 v[112:115], v240 offset:32
	ds_read_b128 v[116:119], v240 offset:16
	s_nop 0
	ds_read_b128 v[96:99], v240
	s_waitcnt lgkmcnt(1)
	v_mul_f32_e32 v95, v142, v95
	v_pk_mul_f32 v[92:93], v[142:143], v[92:93] op_sel_hi:[0,1]
	v_pk_mul_f32 v[90:91], v[142:143], v[90:91] op_sel_hi:[0,1]
	v_pk_mul_f32 v[88:89], v[142:143], v[88:89] op_sel_hi:[0,1]
	s_waitcnt lgkmcnt(0)
	v_mul_f32_e32 v82, v82, v108
	v_mov_b32_e32 v122, v96
	v_mov_b32_e32 v123, v98
	v_mov_b32_e32 v98, v97
	v_mov_b32_e32 v96, v116
	v_mov_b32_e32 v97, v118
	v_pk_mul_f32 v[86:87], v[86:87], v[96:97]
	v_mov_b32_e32 v96, v112
	v_mov_b32_e32 v97, v114
	v_pk_mul_f32 v[80:81], v[80:81], v[96:97]
	v_mul_f32_e32 v96, v95, v109
	s_waitcnt lgkmcnt(0)
	v_mul_f32_e32 v95, v142, v94
	v_mov_b32_e32 v94, v83
	v_pk_mul_f32 v[94:95], v[94:95], v[110:111]
	v_pk_mul_f32 v[84:85], v[84:85], v[122:123]
	v_mov_b32_e32 v118, v117
	v_mov_b32_e32 v114, v113
	v_mov_b32_e32 v83, v95
	v_mov_b32_e32 v97, v94
	v_pk_fma_f32 v[84:85], v[92:93], v[98:99], v[84:85]
	v_pk_fma_f32 v[86:87], v[90:91], v[118:119], v[86:87]
	v_pk_fma_f32 v[80:81], v[88:89], v[114:115], v[80:81]
	v_pk_add_f32 v[82:83], v[82:83], v[96:97]

;     __device__ __forceinline__ void operator()(AccRef acc, const pg8::Unit& u, int wr, int wc, int, int) const {
;     ...
;                 const int row = pm * 256 + ai * 128 + wr * 64 + m * 16 + fr;
;                 const float rstd = __builtin_amdgcn_rsqf(sq[ai][m] * (1.0f / DM) + EPS) * (isq ? QSCALE : 1.0f);
;                 const int pos = samp ? 2048 + ((row - MP) & 63) : (row & 16383);
; #pragma unroll
;                 for (int bj = 0; bj < 2; ++bj) {
;                     const int c0 = pn * 256 + bj * 128 + wc * 32 + 8 * fq;
;                     float v[8];
; #pragma unroll
;                     for (int j = 0; j < 4; ++j) { v[j] = acc[ai][bj][m][0][j] * rstd; v[4 + j] = acc[ai][bj][m][1][j] * rstd; }
;                     const bool ropet = (pn == 6 || pn == 7 || (pn == 8 && bj == 0)) && ((wc & 1) == 0);
;                     if (ropet) {
;                         float pv[8];
; #pragma unroll
;                         for (int j = 0; j < 8; ++j) pv[j] = __shfl_xor(v[j], 16);
;                         if (fq < 2) {
;                             const f32x4* cs = (const f32x4*)(rope + (size_t)pos * 16);
;                             const float sg = (fq == 0) ? -1.f : 1.f;
; #pragma unroll
;                             for (int jj = 0; jj < 4; ++jj) { const f32x4 t = cs[jj];
;                                 v[2 * jj] = v[2 * jj] * t[0] + sg * pv[2 * jj] * t[1];
;                                 v[2 * jj + 1] = v[2 * jj + 1] * t[2] + sg * pv[2 * jj + 1] * t[3]; }
;                         }
.LBB0_206:
	s_nop 1
	v_fmamk_f32 v80, v180, 0x3a800000, v174
	v_rsq_f32_e32 v80, v80
	v_or_b32_e32 v91, 0x830, v177
	v_and_b32_e32 v83, 0x3fff, v150
	v_cndmask_b32_e64 v81, v83, v91, s[4:5]
	v_mul_f32_e32 v82, v151, v80
	v_lshlrev_b32_e32 v136, 6, v81
	v_lshl_add_u64 v[80:81], s[96:97], 0, v[136:137]
	v_pk_mul_f32 v[76:77], v[76:77], v[82:83] op_sel_hi:[1,0]
	v_pk_mul_f32 v[72:73], v[72:73], v[82:83] op_sel_hi:[1,0]
	v_pk_mul_f32 v[78:79], v[78:79], v[82:83] op_sel_hi:[1,0]
	s_and_b64 vcc, exec, s[10:11]
	v_pk_mul_f32 v[74:75], v[74:75], v[82:83] op_sel_hi:[1,0]
	s_cbranch_vccnz .LBB0_210
	ds_bpermute_b32 v88, v168, v76
	ds_bpermute_b32 v89, v168, v77
	ds_bpermute_b32 v86, v168, v78
	ds_bpermute_b32 v87, v168, v79
	ds_bpermute_b32 v84, v168, v72
	ds_bpermute_b32 v85, v168, v73
	ds_bpermute_b32 v92, v168, v74
	ds_bpermute_b32 v90, v168, v75
	s_and_saveexec_b64 s[56:57], s[6:7]
	s_cbranch_execz .LBB0_209
	s_waitcnt lgkmcnt(8)
	v_subrev_u32_e32 v240, s32, v80
	ds_read_b128 v[94:97], v240 offset:48
	ds_read_b128 v[98:101], v240 offset:32
	ds_read_b128 v[102:105], v240 offset:16
	ds_read_b128 v[108:111], v240
	s_waitcnt lgkmcnt(1)
	v_mul_f32_e32 v92, v142, v92
	v_pk_mul_f32 v[88:89], v[142:143], v[88:89] op_sel_hi:[0,1]
	v_pk_mul_f32 v[86:87], v[142:143], v[86:87] op_sel_hi:[0,1]
	v_pk_mul_f32 v[84:85], v[142:143], v[84:85] op_sel_hi:[0,1]
	s_waitcnt lgkmcnt(0)
	v_mul_f32_e32 v74, v74, v94
	v_mul_f32_e32 v92, v92, v95
	s_waitcnt lgkmcnt(0)
	v_mul_f32_e32 v95, v142, v90
	v_mov_b32_e32 v94, v75
	v_mov_b32_e32 v112, v108
	v_mov_b32_e32 v113, v110
	v_mov_b32_e32 v110, v109
	v_mov_b32_e32 v108, v102
	v_mov_b32_e32 v109, v104
	v_mov_b32_e32 v104, v103
	v_mov_b32_e32 v102, v98
	v_mov_b32_e32 v103, v100
	v_pk_mul_f32 v[94:95], v[94:95], v[96:97]
	v_pk_mul_f32 v[76:77], v[76:77], v[112:113]
	v_pk_mul_f32 v[78:79], v[78:79], v[108:109]
	v_pk_mul_f32 v[72:73], v[72:73], v[102:103]
	v_mov_b32_e32 v100, v99
	v_mov_b32_e32 v75, v95
	v_mov_b32_e32 v93, v94
	v_pk_fma_f32 v[76:77], v[88:89], v[110:111], v[76:77]
	v_pk_fma_f32 v[78:79], v[86:87], v[104:105], v[78:79]
	v_pk_fma_f32 v[72:73], v[84:85], v[100:101], v[72:73]
	v_pk_add_f32 v[74:75], v[74:75], v[92:93]

;     __device__ __forceinline__ void operator()(AccRef acc, const pg8::Unit& u, int wr, int wc, int, int) const {
;     ...
;                 const int row = pm * 256 + ai * 128 + wr * 64 + m * 16 + fr;
;                 const float rstd = __builtin_amdgcn_rsqf(sq[ai][m] * (1.0f / DM) + EPS) * (isq ? QSCALE : 1.0f);
;                 const int pos = samp ? 2048 + ((row - MP) & 63) : (row & 16383);
; #pragma unroll
;                 for (int bj = 0; bj < 2; ++bj) {
;                     const int c0 = pn * 256 + bj * 128 + wc * 32 + 8 * fq;
;                     float v[8];
; #pragma unroll
;                     for (int j = 0; j < 4; ++j) { v[j] = acc[ai][bj][m][0][j] * rstd; v[4 + j] = acc[ai][bj][m][1][j] * rstd; }
;                     const bool ropet = (pn == 6 || pn == 7 || (pn == 8 && bj == 0)) && ((wc & 1) == 0);
;                     if (ropet) {
;                         float pv[8];
; #pragma unroll
;                         for (int j = 0; j < 8; ++j) pv[j] = __shfl_xor(v[j], 16);
;                         if (fq < 2) {
;                             const f32x4* cs = (const f32x4*)(rope + (size_t)pos * 16);
;                             const float sg = (fq == 0) ? -1.f : 1.f;
; #pragma unroll
;                             for (int jj = 0; jj < 4; ++jj) { const f32x4 t = cs[jj];
;                                 v[2 * jj] = v[2 * jj] * t[0] + sg * pv[2 * jj] * t[1];
;                                 v[2 * jj + 1] = v[2 * jj + 1] * t[2] + sg * pv[2 * jj + 1] * t[3]; }
;                         }
.LBB0_214:
	v_mov_b32_e32 v83, v82
	v_pk_mul_f32 v[68:69], v[68:69], v[82:83]
	v_pk_mul_f32 v[64:65], v[64:65], v[82:83]
	v_pk_mul_f32 v[70:71], v[70:71], v[82:83]
	s_and_b64 vcc, exec, s[12:13]
	v_pk_mul_f32 v[66:67], v[66:67], v[82:83]
	s_cbranch_vccnz .LBB0_218
	ds_bpermute_b32 v76, v168, v68
	ds_bpermute_b32 v77, v168, v69
	ds_bpermute_b32 v74, v168, v70
	ds_bpermute_b32 v75, v168, v71
	ds_bpermute_b32 v72, v168, v64
	ds_bpermute_b32 v73, v168, v65
	ds_bpermute_b32 v79, v168, v66
	ds_bpermute_b32 v78, v168, v67
	s_and_saveexec_b64 s[56:57], s[6:7]
	s_cbranch_execz .LBB0_217
	v_subrev_u32_e32 v240, s32, v80
	ds_read_b128 v[92:95], v240 offset:48
	ds_read_b128 v[96:99], v240 offset:32
	ds_read_b128 v[100:103], v240 offset:16
	s_nop 0
	ds_read_b128 v[80:83], v240
	s_waitcnt lgkmcnt(1)
	v_mul_f32_e32 v79, v142, v79
	v_pk_mul_f32 v[76:77], v[142:143], v[76:77] op_sel_hi:[0,1]
	v_pk_mul_f32 v[74:75], v[142:143], v[74:75] op_sel_hi:[0,1]
	v_pk_mul_f32 v[72:73], v[142:143], v[72:73] op_sel_hi:[0,1]
	s_waitcnt lgkmcnt(0)
	v_mul_f32_e32 v66, v66, v92
	v_mov_b32_e32 v104, v80
	v_mov_b32_e32 v105, v82
	v_mov_b32_e32 v82, v81
	v_mov_b32_e32 v80, v100
	v_mov_b32_e32 v81, v102
	v_pk_mul_f32 v[70:71], v[70:71], v[80:81]
	v_mov_b32_e32 v80, v96
	v_mov_b32_e32 v81, v98
	v_pk_mul_f32 v[64:65], v[64:65], v[80:81]
	v_mul_f32_e32 v80, v79, v93
	s_waitcnt lgkmcnt(0)
	v_mul_f32_e32 v79, v142, v78
	v_mov_b32_e32 v78, v67
	v_pk_mul_f32 v[78:79], v[78:79], v[94:95]
	v_pk_mul_f32 v[68:69], v[68:69], v[104:105]
	v_mov_b32_e32 v102, v101
	v_mov_b32_e32 v98, v97
	v_mov_b32_e32 v67, v79
	v_mov_b32_e32 v81, v78
	v_pk_fma_f32 v[68:69], v[76:77], v[82:83], v[68:69]
	v_pk_fma_f32 v[70:71], v[74:75], v[102:103], v[70:71]
	v_pk_fma_f32 v[64:65], v[72:73], v[98:99], v[64:65]
	v_pk_add_f32 v[66:67], v[66:67], v[80:81]

;     __device__ __forceinline__ void operator()(AccRef acc, const pg8::Unit& u, int wr, int wc, int, int) const {
;     ...
;                 const int row = pm * 256 + ai * 128 + wr * 64 + m * 16 + fr;
;                 const float rstd = __builtin_amdgcn_rsqf(sq[ai][m] * (1.0f / DM) + EPS) * (isq ? QSCALE : 1.0f);
;                 const int pos = samp ? 2048 + ((row - MP) & 63) : (row & 16383);
; #pragma unroll
;                 for (int bj = 0; bj < 2; ++bj) {
;                     const int c0 = pn * 256 + bj * 128 + wc * 32 + 8 * fq;
;                     float v[8];
; #pragma unroll
;                     for (int j = 0; j < 4; ++j) { v[j] = acc[ai][bj][m][0][j] * rstd; v[4 + j] = acc[ai][bj][m][1][j] * rstd; }
;                     const bool ropet = (pn == 6 || pn == 7 || (pn == 8 && bj == 0)) && ((wc & 1) == 0);
;                     if (ropet) {
;                         float pv[8];
; #pragma unroll
;                         for (int j = 0; j < 8; ++j) pv[j] = __shfl_xor(v[j], 16);
;                         if (fq < 2) {
;                             const f32x4* cs = (const f32x4*)(rope + (size_t)pos * 16);
;                             const float sg = (fq == 0) ? -1.f : 1.f;
; #pragma unroll
;                             for (int jj = 0; jj < 4; ++jj) { const f32x4 t = cs[jj];
;                                 v[2 * jj] = v[2 * jj] * t[0] + sg * pv[2 * jj] * t[1];
;                                 v[2 * jj + 1] = v[2 * jj + 1] * t[2] + sg * pv[2 * jj + 1] * t[3]; }
;                         }
.LBB0_222:
	s_nop 1
	v_fmamk_f32 v64, v178, 0x3a800000, v174
	v_rsq_f32_e32 v64, v64
	s_add_i32 s36, s53, 0x80
	v_mov_b32_e32 v65, s36
	v_bitop3_b32 v67, v177, s70, v65 bitop3:0xc8
	v_mul_f32_e32 v66, v151, v64
	v_cndmask_b32_e64 v64, v67, v179, s[4:5]
	v_lshlrev_b32_e32 v136, 6, v64
	v_lshl_add_u64 v[64:65], s[96:97], 0, v[136:137]
	v_pk_mul_f32 v[60:61], v[60:61], v[66:67] op_sel_hi:[1,0]
	v_pk_mul_f32 v[56:57], v[56:57], v[66:67] op_sel_hi:[1,0]
	v_pk_mul_f32 v[62:63], v[62:63], v[66:67] op_sel_hi:[1,0]
	s_and_b64 vcc, exec, s[10:11]
	v_pk_mul_f32 v[58:59], v[58:59], v[66:67] op_sel_hi:[1,0]
	s_cbranch_vccnz .LBB0_226
	ds_bpermute_b32 v72, v168, v60
	ds_bpermute_b32 v73, v168, v61
	ds_bpermute_b32 v70, v168, v62
	ds_bpermute_b32 v71, v168, v63
	ds_bpermute_b32 v68, v168, v56
	ds_bpermute_b32 v69, v168, v57
	ds_bpermute_b32 v75, v168, v58
	ds_bpermute_b32 v74, v168, v59
	s_and_saveexec_b64 s[14:15], s[6:7]
	s_cbranch_execz .LBB0_225
	s_waitcnt lgkmcnt(8)
	v_subrev_u32_e32 v240, s32, v64
	ds_read_b128 v[76:79], v240 offset:48
	ds_read_b128 v[80:83], v240 offset:32
	ds_read_b128 v[84:87], v240 offset:16
	ds_read_b128 v[92:95], v240
	s_waitcnt lgkmcnt(1)
	v_mul_f32_e32 v75, v142, v75
	v_pk_mul_f32 v[72:73], v[142:143], v[72:73] op_sel_hi:[0,1]
	v_pk_mul_f32 v[70:71], v[142:143], v[70:71] op_sel_hi:[0,1]
	v_pk_mul_f32 v[68:69], v[142:143], v[68:69] op_sel_hi:[0,1]
	s_waitcnt lgkmcnt(0)
	v_mul_f32_e32 v58, v58, v76
	v_mul_f32_e32 v76, v75, v77
	s_waitcnt lgkmcnt(0)
	v_mul_f32_e32 v75, v142, v74
	v_mov_b32_e32 v88, v92
	v_mov_b32_e32 v89, v94
	v_mov_b32_e32 v74, v59
	v_pk_mul_f32 v[60:61], v[60:61], v[88:89]
	v_mov_b32_e32 v88, v84
	v_mov_b32_e32 v89, v86
	v_mov_b32_e32 v86, v85
	v_mov_b32_e32 v84, v80
	v_mov_b32_e32 v85, v82
	v_pk_mul_f32 v[74:75], v[74:75], v[78:79]
	v_mov_b32_e32 v94, v93
	v_pk_mul_f32 v[62:63], v[62:63], v[88:89]
	v_pk_mul_f32 v[56:57], v[56:57], v[84:85]
	v_mov_b32_e32 v82, v81
	v_mov_b32_e32 v59, v75
	v_mov_b32_e32 v77, v74
	v_pk_fma_f32 v[60:61], v[72:73], v[94:95], v[60:61]
	v_pk_fma_f32 v[62:63], v[70:71], v[86:87], v[62:63]
	v_pk_fma_f32 v[56:57], v[68:69], v[82:83], v[56:57]
	v_pk_add_f32 v[58:59], v[58:59], v[76:77]

;     __device__ __forceinline__ void operator()(AccRef acc, const pg8::Unit& u, int wr, int wc, int, int) const {
;     ...
;                 const int row = pm * 256 + ai * 128 + wr * 64 + m * 16 + fr;
;                 const float rstd = __builtin_amdgcn_rsqf(sq[ai][m] * (1.0f / DM) + EPS) * (isq ? QSCALE : 1.0f);
;                 const int pos = samp ? 2048 + ((row - MP) & 63) : (row & 16383);
; #pragma unroll
;                 for (int bj = 0; bj < 2; ++bj) {
;                     const int c0 = pn * 256 + bj * 128 + wc * 32 + 8 * fq;
;                     float v[8];
; #pragma unroll
;                     for (int j = 0; j < 4; ++j) { v[j] = acc[ai][bj][m][0][j] * rstd; v[4 + j] = acc[ai][bj][m][1][j] * rstd; }
;                     const bool ropet = (pn == 6 || pn == 7 || (pn == 8 && bj == 0)) && ((wc & 1) == 0);
;                     if (ropet) {
;                         float pv[8];
; #pragma unroll
;                         for (int j = 0; j < 8; ++j) pv[j] = __shfl_xor(v[j], 16);
;                         if (fq < 2) {
;                             const f32x4* cs = (const f32x4*)(rope + (size_t)pos * 16);
;                             const float sg = (fq == 0) ? -1.f : 1.f;
; #pragma unroll
;                             for (int jj = 0; jj < 4; ++jj) { const f32x4 t = cs[jj];
;                                 v[2 * jj] = v[2 * jj] * t[0] + sg * pv[2 * jj] * t[1];
;                                 v[2 * jj + 1] = v[2 * jj + 1] * t[2] + sg * pv[2 * jj + 1] * t[3]; }
;                         }
.LBB0_230:
	v_mov_b32_e32 v67, v66
	v_pk_mul_f32 v[52:53], v[52:53], v[66:67]
	v_pk_mul_f32 v[48:49], v[48:49], v[66:67]
	v_pk_mul_f32 v[54:55], v[54:55], v[66:67]
	s_and_b64 vcc, exec, s[12:13]
	v_pk_mul_f32 v[50:51], v[50:51], v[66:67]
	s_cbranch_vccnz .LBB0_234
	ds_bpermute_b32 v60, v168, v52
	ds_bpermute_b32 v61, v168, v53
	ds_bpermute_b32 v58, v168, v54
	ds_bpermute_b32 v59, v168, v55
	ds_bpermute_b32 v56, v168, v48
	ds_bpermute_b32 v57, v168, v49
	ds_bpermute_b32 v63, v168, v50
	ds_bpermute_b32 v62, v168, v51
	s_and_saveexec_b64 s[54:55], s[6:7]
	s_cbranch_execz .LBB0_233
	v_subrev_u32_e32 v240, s32, v64
	ds_read_b128 v[76:79], v240 offset:48
	ds_read_b128 v[80:83], v240 offset:32
	ds_read_b128 v[84:87], v240 offset:16
	s_nop 0
	ds_read_b128 v[64:67], v240
	s_waitcnt lgkmcnt(1)
	v_mul_f32_e32 v63, v142, v63
	v_pk_mul_f32 v[60:61], v[142:143], v[60:61] op_sel_hi:[0,1]
	v_pk_mul_f32 v[58:59], v[142:143], v[58:59] op_sel_hi:[0,1]
	v_pk_mul_f32 v[56:57], v[142:143], v[56:57] op_sel_hi:[0,1]
	s_waitcnt lgkmcnt(0)
	v_mul_f32_e32 v50, v50, v76
	v_mov_b32_e32 v88, v64
	v_mov_b32_e32 v89, v66
	v_mov_b32_e32 v66, v65
	v_mov_b32_e32 v64, v84
	v_mov_b32_e32 v65, v86
	v_pk_mul_f32 v[54:55], v[54:55], v[64:65]
	v_mov_b32_e32 v64, v80
	v_mov_b32_e32 v65, v82
	v_pk_mul_f32 v[48:49], v[48:49], v[64:65]
	v_mul_f32_e32 v64, v63, v77
	s_waitcnt lgkmcnt(0)
	v_mul_f32_e32 v63, v142, v62
	v_mov_b32_e32 v62, v51
	v_pk_mul_f32 v[62:63], v[62:63], v[78:79]
	v_pk_mul_f32 v[52:53], v[52:53], v[88:89]
	v_mov_b32_e32 v86, v85
	v_mov_b32_e32 v82, v81
	v_mov_b32_e32 v51, v63
	v_mov_b32_e32 v65, v62
	v_pk_fma_f32 v[52:53], v[60:61], v[66:67], v[52:53]
	v_pk_fma_f32 v[54:55], v[58:59], v[86:87], v[54:55]
	v_pk_fma_f32 v[48:49], v[56:57], v[82:83], v[48:49]
	v_pk_add_f32 v[50:51], v[50:51], v[64:65]

;     __device__ __forceinline__ void operator()(AccRef acc, const pg8::Unit& u, int wr, int wc, int, int) const {
;     ...
;                 const int row = pm * 256 + ai * 128 + wr * 64 + m * 16 + fr;
;                 const float rstd = __builtin_amdgcn_rsqf(sq[ai][m] * (1.0f / DM) + EPS) * (isq ? QSCALE : 1.0f);
;                 const int pos = samp ? 2048 + ((row - MP) & 63) : (row & 16383);
; #pragma unroll
;                 for (int bj = 0; bj < 2; ++bj) {
;                     const int c0 = pn * 256 + bj * 128 + wc * 32 + 8 * fq;
;                     float v[8];
; #pragma unroll
;                     for (int j = 0; j < 4; ++j) { v[j] = acc[ai][bj][m][0][j] * rstd; v[4 + j] = acc[ai][bj][m][1][j] * rstd; }
;                     const bool ropet = (pn == 6 || pn == 7 || (pn == 8 && bj == 0)) && ((wc & 1) == 0);
;                     if (ropet) {
;                         float pv[8];
; #pragma unroll
;                         for (int j = 0; j < 8; ++j) pv[j] = __shfl_xor(v[j], 16);
;                         if (fq < 2) {
;                             const f32x4* cs = (const f32x4*)(rope + (size_t)pos * 16);
;                             const float sg = (fq == 0) ? -1.f : 1.f;
; #pragma unroll
;                             for (int jj = 0; jj < 4; ++jj) { const f32x4 t = cs[jj];
;                                 v[2 * jj] = v[2 * jj] * t[0] + sg * pv[2 * jj] * t[1];
;                                 v[2 * jj + 1] = v[2 * jj + 1] * t[2] + sg * pv[2 * jj + 1] * t[3]; }
;                         }
.LBB0_238:
	s_nop 1
	v_fmamk_f32 v48, v176, 0x3a800000, v174
	v_rsq_f32_e32 v48, v48
	s_movk_i32 s36, 0x3fdf
	v_bitop3_b32 v51, v74, s36, 16 bitop3:0xc8
	v_cndmask_b32_e64 v49, v51, v125, s[4:5]
	v_lshlrev_b32_e32 v136, 6, v49
	v_mul_f32_e32 v50, v151, v48
	v_lshl_add_u64 v[48:49], s[96:97], 0, v[136:137]
	v_pk_mul_f32 v[44:45], v[44:45], v[50:51] op_sel_hi:[1,0]
	v_pk_mul_f32 v[40:41], v[40:41], v[50:51] op_sel_hi:[1,0]
	v_pk_mul_f32 v[46:47], v[46:47], v[50:51] op_sel_hi:[1,0]
	s_and_b64 vcc, exec, s[10:11]
	v_pk_mul_f32 v[42:43], v[42:43], v[50:51] op_sel_hi:[1,0]
	s_cbranch_vccnz .LBB0_242
	ds_bpermute_b32 v56, v168, v44
	ds_bpermute_b32 v57, v168, v45
	ds_bpermute_b32 v54, v168, v46
	ds_bpermute_b32 v55, v168, v47
	ds_bpermute_b32 v52, v168, v40
	ds_bpermute_b32 v53, v168, v41
	ds_bpermute_b32 v59, v168, v42
	ds_bpermute_b32 v58, v168, v43
	s_and_saveexec_b64 s[54:55], s[6:7]
	s_cbranch_execz .LBB0_241
	s_waitcnt lgkmcnt(8)
	v_subrev_u32_e32 v240, s32, v48
	ds_read_b128 v[60:63], v240 offset:48
	ds_read_b128 v[64:67], v240 offset:32
	ds_read_b128 v[68:71], v240 offset:16
	ds_read_b128 v[76:79], v240
	s_waitcnt lgkmcnt(1)
	v_mul_f32_e32 v59, v142, v59
	v_pk_mul_f32 v[56:57], v[142:143], v[56:57] op_sel_hi:[0,1]
	v_pk_mul_f32 v[54:55], v[142:143], v[54:55] op_sel_hi:[0,1]
	v_pk_mul_f32 v[52:53], v[142:143], v[52:53] op_sel_hi:[0,1]
	s_waitcnt lgkmcnt(0)
	v_mul_f32_e32 v42, v42, v60
	v_mul_f32_e32 v60, v59, v61
	s_waitcnt lgkmcnt(0)
	v_mul_f32_e32 v59, v142, v58
	v_mov_b32_e32 v72, v76
	v_mov_b32_e32 v73, v78
	v_mov_b32_e32 v58, v43
	v_pk_mul_f32 v[44:45], v[44:45], v[72:73]
	v_mov_b32_e32 v72, v68
	v_mov_b32_e32 v73, v70
	v_mov_b32_e32 v70, v69
	v_mov_b32_e32 v68, v64
	v_mov_b32_e32 v69, v66
	v_pk_mul_f32 v[58:59], v[58:59], v[62:63]
	v_mov_b32_e32 v78, v77
	v_pk_mul_f32 v[46:47], v[46:47], v[72:73]
	v_pk_mul_f32 v[40:41], v[40:41], v[68:69]
	v_mov_b32_e32 v66, v65
	v_mov_b32_e32 v43, v59
	v_mov_b32_e32 v61, v58
	v_pk_fma_f32 v[44:45], v[56:57], v[78:79], v[44:45]
	v_pk_fma_f32 v[46:47], v[54:55], v[70:71], v[46:47]
	v_pk_fma_f32 v[40:41], v[52:53], v[66:67], v[40:41]
	v_pk_add_f32 v[42:43], v[42:43], v[60:61]

;     __device__ __forceinline__ void operator()(AccRef acc, const pg8::Unit& u, int wr, int wc, int, int) const {
;     ...
;                 const int row = pm * 256 + ai * 128 + wr * 64 + m * 16 + fr;
;                 const float rstd = __builtin_amdgcn_rsqf(sq[ai][m] * (1.0f / DM) + EPS) * (isq ? QSCALE : 1.0f);
;                 const int pos = samp ? 2048 + ((row - MP) & 63) : (row & 16383);
; #pragma unroll
;                 for (int bj = 0; bj < 2; ++bj) {
;                     const int c0 = pn * 256 + bj * 128 + wc * 32 + 8 * fq;
;                     float v[8];
; #pragma unroll
;                     for (int j = 0; j < 4; ++j) { v[j] = acc[ai][bj][m][0][j] * rstd; v[4 + j] = acc[ai][bj][m][1][j] * rstd; }
;                     const bool ropet = (pn == 6 || pn == 7 || (pn == 8 && bj == 0)) && ((wc & 1) == 0);
;                     if (ropet) {
;                         float pv[8];
; #pragma unroll
;                         for (int j = 0; j < 8; ++j) pv[j] = __shfl_xor(v[j], 16);
;                         if (fq < 2) {
;                             const f32x4* cs = (const f32x4*)(rope + (size_t)pos * 16);
;                             const float sg = (fq == 0) ? -1.f : 1.f;
; #pragma unroll
;                             for (int jj = 0; jj < 4; ++jj) { const f32x4 t = cs[jj];
;                                 v[2 * jj] = v[2 * jj] * t[0] + sg * pv[2 * jj] * t[1];
;                                 v[2 * jj + 1] = v[2 * jj + 1] * t[2] + sg * pv[2 * jj + 1] * t[3]; }
;                         }
.LBB0_246:
	v_mov_b32_e32 v51, v50
	v_pk_mul_f32 v[36:37], v[36:37], v[50:51]
	v_pk_mul_f32 v[32:33], v[32:33], v[50:51]
	v_pk_mul_f32 v[38:39], v[38:39], v[50:51]
	s_and_b64 vcc, exec, s[12:13]
	v_pk_mul_f32 v[34:35], v[34:35], v[50:51]
	s_cbranch_vccnz .LBB0_250
	ds_bpermute_b32 v44, v168, v36
	ds_bpermute_b32 v45, v168, v37
	ds_bpermute_b32 v42, v168, v38
	ds_bpermute_b32 v43, v168, v39
	ds_bpermute_b32 v40, v168, v32
	ds_bpermute_b32 v41, v168, v33
	ds_bpermute_b32 v47, v168, v34
	ds_bpermute_b32 v46, v168, v35
	s_and_saveexec_b64 s[54:55], s[6:7]
	s_cbranch_execz .LBB0_249
	v_subrev_u32_e32 v240, s32, v48
	ds_read_b128 v[58:61], v240 offset:48
	ds_read_b128 v[62:65], v240 offset:32
	ds_read_b128 v[66:69], v240 offset:16
	s_nop 0
	ds_read_b128 v[48:51], v240
	s_waitcnt lgkmcnt(1)
	v_mul_f32_e32 v47, v142, v47
	v_pk_mul_f32 v[44:45], v[142:143], v[44:45] op_sel_hi:[0,1]
	v_pk_mul_f32 v[42:43], v[142:143], v[42:43] op_sel_hi:[0,1]
	v_pk_mul_f32 v[40:41], v[142:143], v[40:41] op_sel_hi:[0,1]
	s_waitcnt lgkmcnt(0)
	v_mul_f32_e32 v34, v34, v58
	v_mov_b32_e32 v70, v48
	v_mov_b32_e32 v71, v50
	v_mov_b32_e32 v50, v49
	v_mov_b32_e32 v48, v66
	v_mov_b32_e32 v49, v68
	v_pk_mul_f32 v[38:39], v[38:39], v[48:49]
	v_mov_b32_e32 v48, v62
	v_mov_b32_e32 v49, v64
	v_pk_mul_f32 v[32:33], v[32:33], v[48:49]
	v_mul_f32_e32 v48, v47, v59
	s_waitcnt lgkmcnt(0)
	v_mul_f32_e32 v47, v142, v46
	v_mov_b32_e32 v46, v35
	v_pk_mul_f32 v[46:47], v[46:47], v[60:61]
	v_pk_mul_f32 v[36:37], v[36:37], v[70:71]
	v_mov_b32_e32 v68, v67
	v_mov_b32_e32 v64, v63
	v_mov_b32_e32 v35, v47
	v_mov_b32_e32 v49, v46
	v_pk_fma_f32 v[36:37], v[44:45], v[50:51], v[36:37]
	v_pk_fma_f32 v[38:39], v[42:43], v[68:69], v[38:39]
	v_pk_fma_f32 v[32:33], v[40:41], v[64:65], v[32:33]
	v_pk_add_f32 v[34:35], v[34:35], v[48:49]

;     __device__ __forceinline__ void operator()(AccRef acc, const pg8::Unit& u, int wr, int wc, int, int) const {
;     ...
;                 const int row = pm * 256 + ai * 128 + wr * 64 + m * 16 + fr;
;                 const float rstd = __builtin_amdgcn_rsqf(sq[ai][m] * (1.0f / DM) + EPS) * (isq ? QSCALE : 1.0f);
;                 const int pos = samp ? 2048 + ((row - MP) & 63) : (row & 16383);
; #pragma unroll
;                 for (int bj = 0; bj < 2; ++bj) {
;                     const int c0 = pn * 256 + bj * 128 + wc * 32 + 8 * fq;
;                     float v[8];
; #pragma unroll
;                     for (int j = 0; j < 4; ++j) { v[j] = acc[ai][bj][m][0][j] * rstd; v[4 + j] = acc[ai][bj][m][1][j] * rstd; }
;                     const bool ropet = (pn == 6 || pn == 7 || (pn == 8 && bj == 0)) && ((wc & 1) == 0);
;                     if (ropet) {
;                         float pv[8];
; #pragma unroll
;                         for (int j = 0; j < 8; ++j) pv[j] = __shfl_xor(v[j], 16);
;                         if (fq < 2) {
;                             const f32x4* cs = (const f32x4*)(rope + (size_t)pos * 16);
;                             const float sg = (fq == 0) ? -1.f : 1.f;
; #pragma unroll
;                             for (int jj = 0; jj < 4; ++jj) { const f32x4 t = cs[jj];
;                                 v[2 * jj] = v[2 * jj] * t[0] + sg * pv[2 * jj] * t[1];
;                                 v[2 * jj + 1] = v[2 * jj + 1] * t[2] + sg * pv[2 * jj + 1] * t[3]; }
;                         }
.LBB0_254:
	s_nop 1
	v_fmamk_f32 v32, v155, 0x3a800000, v174
	v_rsq_f32_e32 v32, v32
	s_movk_i32 s36, 0x3fef
	v_bitop3_b32 v35, v74, s36, 32 bitop3:0xc8
	v_cndmask_b32_e64 v33, v35, v107, s[4:5]
	v_lshlrev_b32_e32 v136, 6, v33
	v_mul_f32_e32 v34, v151, v32
	v_lshl_add_u64 v[32:33], s[96:97], 0, v[136:137]
	v_pk_mul_f32 v[28:29], v[28:29], v[34:35] op_sel_hi:[1,0]
	v_pk_mul_f32 v[24:25], v[24:25], v[34:35] op_sel_hi:[1,0]
	v_pk_mul_f32 v[30:31], v[30:31], v[34:35] op_sel_hi:[1,0]
	s_and_b64 vcc, exec, s[10:11]
	v_pk_mul_f32 v[26:27], v[26:27], v[34:35] op_sel_hi:[1,0]
	s_cbranch_vccnz .LBB0_258
	ds_bpermute_b32 v40, v168, v28
	ds_bpermute_b32 v41, v168, v29
	ds_bpermute_b32 v38, v168, v30
	ds_bpermute_b32 v39, v168, v31
	ds_bpermute_b32 v36, v168, v24
	ds_bpermute_b32 v37, v168, v25
	ds_bpermute_b32 v43, v168, v26
	ds_bpermute_b32 v42, v168, v27
	s_and_saveexec_b64 s[54:55], s[6:7]
	s_cbranch_execz .LBB0_257
	s_waitcnt lgkmcnt(8)
	v_subrev_u32_e32 v240, s32, v32
	ds_read_b128 v[44:47], v240 offset:48
	ds_read_b128 v[48:51], v240 offset:32
	ds_read_b128 v[52:55], v240 offset:16
	ds_read_b128 v[56:59], v240
	s_waitcnt lgkmcnt(1)
	v_mul_f32_e32 v43, v142, v43
	v_pk_mul_f32 v[40:41], v[142:143], v[40:41] op_sel_hi:[0,1]
	v_pk_mul_f32 v[38:39], v[142:143], v[38:39] op_sel_hi:[0,1]
	v_pk_mul_f32 v[36:37], v[142:143], v[36:37] op_sel_hi:[0,1]
	s_waitcnt lgkmcnt(0)
	v_mul_f32_e32 v26, v26, v44
	v_mul_f32_e32 v44, v43, v45
	s_waitcnt lgkmcnt(0)
	v_mul_f32_e32 v43, v142, v42
	v_mov_b32_e32 v42, v27
	v_mov_b32_e32 v60, v56
	v_mov_b32_e32 v61, v58
	v_mov_b32_e32 v58, v57
	v_mov_b32_e32 v56, v52
	v_mov_b32_e32 v57, v54
	v_mov_b32_e32 v54, v53
	v_mov_b32_e32 v52, v48
	v_mov_b32_e32 v53, v50
	v_pk_mul_f32 v[42:43], v[42:43], v[46:47]
	v_pk_mul_f32 v[28:29], v[28:29], v[60:61]
	v_pk_mul_f32 v[30:31], v[30:31], v[56:57]
	v_pk_mul_f32 v[24:25], v[24:25], v[52:53]
	v_mov_b32_e32 v50, v49
	v_mov_b32_e32 v27, v43
	v_mov_b32_e32 v45, v42
	v_pk_fma_f32 v[28:29], v[40:41], v[58:59], v[28:29]
	v_pk_fma_f32 v[30:31], v[38:39], v[54:55], v[30:31]
	v_pk_fma_f32 v[24:25], v[36:37], v[50:51], v[24:25]
	v_pk_add_f32 v[26:27], v[26:27], v[44:45]

;     __device__ __forceinline__ void operator()(AccRef acc, const pg8::Unit& u, int wr, int wc, int, int) const {
;     ...
;                 const int row = pm * 256 + ai * 128 + wr * 64 + m * 16 + fr;
;                 const float rstd = __builtin_amdgcn_rsqf(sq[ai][m] * (1.0f / DM) + EPS) * (isq ? QSCALE : 1.0f);
;                 const int pos = samp ? 2048 + ((row - MP) & 63) : (row & 16383);
; #pragma unroll
;                 for (int bj = 0; bj < 2; ++bj) {
;                     const int c0 = pn * 256 + bj * 128 + wc * 32 + 8 * fq;
;                     float v[8];
; #pragma unroll
;                     for (int j = 0; j < 4; ++j) { v[j] = acc[ai][bj][m][0][j] * rstd; v[4 + j] = acc[ai][bj][m][1][j] * rstd; }
;                     const bool ropet = (pn == 6 || pn == 7 || (pn == 8 && bj == 0)) && ((wc & 1) == 0);
;                     if (ropet) {
;                         float pv[8];
; #pragma unroll
;                         for (int j = 0; j < 8; ++j) pv[j] = __shfl_xor(v[j], 16);
;                         if (fq < 2) {
;                             const f32x4* cs = (const f32x4*)(rope + (size_t)pos * 16);
;                             const float sg = (fq == 0) ? -1.f : 1.f;
; #pragma unroll
;                             for (int jj = 0; jj < 4; ++jj) { const f32x4 t = cs[jj];
;                                 v[2 * jj] = v[2 * jj] * t[0] + sg * pv[2 * jj] * t[1];
;                                 v[2 * jj + 1] = v[2 * jj + 1] * t[2] + sg * pv[2 * jj + 1] * t[3]; }
;                         }
.LBB0_262:
	v_mov_b32_e32 v35, v34
	v_pk_mul_f32 v[20:21], v[20:21], v[34:35]
	v_pk_mul_f32 v[16:17], v[16:17], v[34:35]
	v_pk_mul_f32 v[22:23], v[22:23], v[34:35]
	s_and_b64 vcc, exec, s[12:13]
	v_pk_mul_f32 v[18:19], v[18:19], v[34:35]
	s_cbranch_vccnz .LBB0_266
	ds_bpermute_b32 v28, v168, v20
	ds_bpermute_b32 v29, v168, v21
	ds_bpermute_b32 v26, v168, v22
	ds_bpermute_b32 v27, v168, v23
	ds_bpermute_b32 v24, v168, v16
	ds_bpermute_b32 v25, v168, v17
	ds_bpermute_b32 v31, v168, v18
	ds_bpermute_b32 v30, v168, v19
	s_and_saveexec_b64 s[54:55], s[6:7]
	s_cbranch_execz .LBB0_265
	v_subrev_u32_e32 v240, s32, v32
	ds_read_b128 v[42:45], v240 offset:48
	ds_read_b128 v[46:49], v240 offset:32
	ds_read_b128 v[50:53], v240 offset:16
	s_nop 0
	ds_read_b128 v[32:35], v240
	s_waitcnt lgkmcnt(1)
	v_mul_f32_e32 v31, v142, v31
	v_pk_mul_f32 v[28:29], v[142:143], v[28:29] op_sel_hi:[0,1]
	v_pk_mul_f32 v[26:27], v[142:143], v[26:27] op_sel_hi:[0,1]
	v_pk_mul_f32 v[24:25], v[142:143], v[24:25] op_sel_hi:[0,1]
	s_waitcnt lgkmcnt(0)
	v_mul_f32_e32 v18, v18, v42
	v_mov_b32_e32 v54, v32
	v_mov_b32_e32 v55, v34
	v_mov_b32_e32 v34, v33
	v_mov_b32_e32 v32, v50
	v_mov_b32_e32 v33, v52
	v_pk_mul_f32 v[22:23], v[22:23], v[32:33]
	v_mov_b32_e32 v32, v46
	v_mov_b32_e32 v33, v48
	v_pk_mul_f32 v[16:17], v[16:17], v[32:33]
	v_mul_f32_e32 v32, v31, v43
	s_waitcnt lgkmcnt(0)
	v_mul_f32_e32 v31, v142, v30
	v_mov_b32_e32 v30, v19
	v_pk_mul_f32 v[30:31], v[30:31], v[44:45]
	v_pk_mul_f32 v[20:21], v[20:21], v[54:55]
	v_mov_b32_e32 v52, v51
	v_mov_b32_e32 v48, v47
	v_mov_b32_e32 v19, v31
	v_mov_b32_e32 v33, v30
	v_pk_fma_f32 v[20:21], v[28:29], v[34:35], v[20:21]
	v_pk_fma_f32 v[22:23], v[26:27], v[52:53], v[22:23]
	v_pk_fma_f32 v[16:17], v[24:25], v[48:49], v[16:17]
	v_pk_add_f32 v[18:19], v[18:19], v[32:33]

;     __device__ __forceinline__ void operator()(AccRef acc, const pg8::Unit& u, int wr, int wc, int, int) const {
;     ...
;                 const int row = pm * 256 + ai * 128 + wr * 64 + m * 16 + fr;
;                 const float rstd = __builtin_amdgcn_rsqf(sq[ai][m] * (1.0f / DM) + EPS) * (isq ? QSCALE : 1.0f);
;                 const int pos = samp ? 2048 + ((row - MP) & 63) : (row & 16383);
; #pragma unroll
;                 for (int bj = 0; bj < 2; ++bj) {
;                     const int c0 = pn * 256 + bj * 128 + wc * 32 + 8 * fq;
;                     float v[8];
; #pragma unroll
;                     for (int j = 0; j < 4; ++j) { v[j] = acc[ai][bj][m][0][j] * rstd; v[4 + j] = acc[ai][bj][m][1][j] * rstd; }
;                     const bool ropet = (pn == 6 || pn == 7 || (pn == 8 && bj == 0)) && ((wc & 1) == 0);
;                     if (ropet) {
;                         float pv[8];
; #pragma unroll
;                         for (int j = 0; j < 8; ++j) pv[j] = __shfl_xor(v[j], 16);
;                         if (fq < 2) {
;                             const f32x4* cs = (const f32x4*)(rope + (size_t)pos * 16);
;                             const float sg = (fq == 0) ? -1.f : 1.f;
; #pragma unroll
;                             for (int jj = 0; jj < 4; ++jj) { const f32x4 t = cs[jj];
;                                 v[2 * jj] = v[2 * jj] * t[0] + sg * pv[2 * jj] * t[1];
;                                 v[2 * jj + 1] = v[2 * jj + 1] * t[2] + sg * pv[2 * jj + 1] * t[3]; }
;                         }
.LBB0_270:
	s_nop 1
	v_fmamk_f32 v16, v153, 0x3a800000, v174
	v_rsq_f32_e32 v16, v16
	s_movk_i32 s36, 0x3fff
	v_bitop3_b32 v19, v74, s36, 48 bitop3:0xc8
	v_cndmask_b32_e64 v17, v19, v91, s[4:5]
	v_lshlrev_b32_e32 v136, 6, v17
	v_mul_f32_e32 v18, v151, v16
	v_lshl_add_u64 v[16:17], s[96:97], 0, v[136:137]
	v_pk_mul_f32 v[12:13], v[12:13], v[18:19] op_sel_hi:[1,0]
	v_pk_mul_f32 v[8:9], v[8:9], v[18:19] op_sel_hi:[1,0]
	v_pk_mul_f32 v[14:15], v[14:15], v[18:19] op_sel_hi:[1,0]
	s_and_b64 vcc, exec, s[10:11]
	v_pk_mul_f32 v[10:11], v[10:11], v[18:19] op_sel_hi:[1,0]
	s_cbranch_vccnz .LBB0_274
	ds_bpermute_b32 v24, v168, v12
	ds_bpermute_b32 v25, v168, v13
	ds_bpermute_b32 v22, v168, v14
	ds_bpermute_b32 v23, v168, v15
	ds_bpermute_b32 v20, v168, v8
	ds_bpermute_b32 v21, v168, v9
	ds_bpermute_b32 v27, v168, v10
	ds_bpermute_b32 v26, v168, v11
	s_and_saveexec_b64 s[10:11], s[6:7]
	s_cbranch_execz .LBB0_273
	s_waitcnt lgkmcnt(8)
	v_subrev_u32_e32 v240, s32, v16
	ds_read_b128 v[28:31], v240 offset:48
	ds_read_b128 v[32:35], v240 offset:32
	ds_read_b128 v[36:39], v240 offset:16
	ds_read_b128 v[40:43], v240
	s_waitcnt lgkmcnt(1)
	v_mul_f32_e32 v27, v142, v27
	v_pk_mul_f32 v[24:25], v[142:143], v[24:25] op_sel_hi:[0,1]
	v_pk_mul_f32 v[22:23], v[142:143], v[22:23] op_sel_hi:[0,1]
	v_pk_mul_f32 v[20:21], v[142:143], v[20:21] op_sel_hi:[0,1]
	s_waitcnt lgkmcnt(0)
	v_mul_f32_e32 v10, v10, v28
	v_mul_f32_e32 v28, v27, v29
	s_waitcnt lgkmcnt(0)
	v_mul_f32_e32 v27, v142, v26
	v_mov_b32_e32 v26, v11
	v_mov_b32_e32 v44, v40
	v_mov_b32_e32 v45, v42
	v_mov_b32_e32 v42, v41
	v_mov_b32_e32 v40, v36
	v_mov_b32_e32 v41, v38
	v_mov_b32_e32 v38, v37
	v_mov_b32_e32 v36, v32
	v_mov_b32_e32 v37, v34
	v_pk_mul_f32 v[26:27], v[26:27], v[30:31]
	v_pk_mul_f32 v[12:13], v[12:13], v[44:45]
	v_pk_mul_f32 v[14:15], v[14:15], v[40:41]
	v_pk_mul_f32 v[8:9], v[8:9], v[36:37]
	v_mov_b32_e32 v34, v33
	v_mov_b32_e32 v11, v27
	v_mov_b32_e32 v29, v26
	v_pk_fma_f32 v[12:13], v[24:25], v[42:43], v[12:13]
	v_pk_fma_f32 v[14:15], v[22:23], v[38:39], v[14:15]
	v_pk_fma_f32 v[8:9], v[20:21], v[34:35], v[8:9]
	v_pk_add_f32 v[10:11], v[10:11], v[28:29]

;     __device__ __forceinline__ void operator()(AccRef acc, const pg8::Unit& u, int wr, int wc, int, int) const {
;     ...
;                 const int row = pm * 256 + ai * 128 + wr * 64 + m * 16 + fr;
;                 const float rstd = __builtin_amdgcn_rsqf(sq[ai][m] * (1.0f / DM) + EPS) * (isq ? QSCALE : 1.0f);
;                 const int pos = samp ? 2048 + ((row - MP) & 63) : (row & 16383);
; #pragma unroll
;                 for (int bj = 0; bj < 2; ++bj) {
;                     const int c0 = pn * 256 + bj * 128 + wc * 32 + 8 * fq;
;                     float v[8];
; #pragma unroll
;                     for (int j = 0; j < 4; ++j) { v[j] = acc[ai][bj][m][0][j] * rstd; v[4 + j] = acc[ai][bj][m][1][j] * rstd; }
;                     const bool ropet = (pn == 6 || pn == 7 || (pn == 8 && bj == 0)) && ((wc & 1) == 0);
;                     if (ropet) {
;                         float pv[8];
; #pragma unroll
;                         for (int j = 0; j < 8; ++j) pv[j] = __shfl_xor(v[j], 16);
;                         if (fq < 2) {
;                             const f32x4* cs = (const f32x4*)(rope + (size_t)pos * 16);
;                             const float sg = (fq == 0) ? -1.f : 1.f;
; #pragma unroll
;                             for (int jj = 0; jj < 4; ++jj) { const f32x4 t = cs[jj];
;                                 v[2 * jj] = v[2 * jj] * t[0] + sg * pv[2 * jj] * t[1];
;                                 v[2 * jj + 1] = v[2 * jj + 1] * t[2] + sg * pv[2 * jj + 1] * t[3]; }
;                         }
.LBB0_278:
	v_mov_b32_e32 v19, v18
	v_pk_mul_f32 v[4:5], v[4:5], v[18:19]
	v_pk_mul_f32 v[0:1], v[0:1], v[18:19]
	v_pk_mul_f32 v[6:7], v[6:7], v[18:19]
	s_and_b64 vcc, exec, s[12:13]
	v_pk_mul_f32 v[2:3], v[2:3], v[18:19]
	s_cbranch_vccnz .LBB0_282
	ds_bpermute_b32 v12, v168, v4
	ds_bpermute_b32 v13, v168, v5
	ds_bpermute_b32 v10, v168, v6
	ds_bpermute_b32 v11, v168, v7
	ds_bpermute_b32 v8, v168, v0
	ds_bpermute_b32 v9, v168, v1
	ds_bpermute_b32 v15, v168, v2
	ds_bpermute_b32 v14, v168, v3
	s_and_saveexec_b64 s[10:11], s[6:7]
	s_cbranch_execz .LBB0_281
	v_subrev_u32_e32 v240, s32, v16
	ds_read_b128 v[26:29], v240 offset:48
	ds_read_b128 v[30:33], v240 offset:32
	ds_read_b128 v[34:37], v240 offset:16
	s_nop 0
	ds_read_b128 v[16:19], v240
	s_waitcnt lgkmcnt(1)
	v_mul_f32_e32 v15, v142, v15
	v_pk_mul_f32 v[12:13], v[142:143], v[12:13] op_sel_hi:[0,1]
	v_pk_mul_f32 v[10:11], v[142:143], v[10:11] op_sel_hi:[0,1]
	v_pk_mul_f32 v[8:9], v[142:143], v[8:9] op_sel_hi:[0,1]
	s_waitcnt lgkmcnt(0)
	v_mul_f32_e32 v2, v2, v26
	v_mov_b32_e32 v38, v16
	v_mov_b32_e32 v39, v18
	v_mov_b32_e32 v18, v17
	v_mov_b32_e32 v16, v34
	v_mov_b32_e32 v17, v36
	v_pk_mul_f32 v[6:7], v[6:7], v[16:17]
	v_mov_b32_e32 v16, v30
	v_mov_b32_e32 v17, v32
	v_pk_mul_f32 v[0:1], v[0:1], v[16:17]
	v_mul_f32_e32 v16, v15, v27
	s_waitcnt lgkmcnt(0)
	v_mul_f32_e32 v15, v142, v14
	v_mov_b32_e32 v14, v3
	v_pk_mul_f32 v[14:15], v[14:15], v[28:29]
	v_pk_mul_f32 v[4:5], v[4:5], v[38:39]
	v_mov_b32_e32 v36, v35
	v_mov_b32_e32 v32, v31
	v_mov_b32_e32 v3, v15
	v_mov_b32_e32 v17, v14
	v_pk_fma_f32 v[4:5], v[12:13], v[18:19], v[4:5]
	v_pk_fma_f32 v[6:7], v[10:11], v[36:37], v[6:7]
	v_pk_fma_f32 v[0:1], v[8:9], v[32:33], v[0:1]
	v_pk_add_f32 v[2:3], v[2:3], v[16:17]

;     __device__ __forceinline__ void operator()(AccRef acc, const pg8::Unit& u, int wr, int wc, int, int) const {
;     ...
; #pragma unroll
;         for (int ai = 0; ai < 2; ++ai)
; #pragma unroll
;             for (int m = 0; m < 4; ++m) sq[ai][m] = ssq[pm * 256 + ai * 128 + wr * 64 + m * 16 + fr];
;         asm volatile("" ::: "memory");
; #pragma unroll
;         for (int ai = 0; ai < 2; ++ai)
; #pragma unroll
;             for (int m = 0; m < 4; ++m) {
;                 const int row = pm * 256 + ai * 128 + wr * 64 + m * 16 + fr;
;                 const float rstd = __builtin_amdgcn_rsqf(sq[ai][m] * (1.0f / DM) + EPS) * (isq ? QSCALE : 1.0f);
;                 const int pos = samp ? 2048 + ((row - MP) & 63) : (row & 16383);
; #pragma unroll
;                 for (int bj = 0; bj < 2; ++bj) {
;                     const int c0 = pn * 256 + bj * 128 + wc * 32 + 8 * fq;
;                     float v[8];
; #pragma unroll
;                     for (int j = 0; j < 4; ++j) { v[j] = acc[ai][bj][m][0][j] * rstd; v[4 + j] = acc[ai][bj][m][1][j] * rstd; }
;                     const bool ropet = (pn == 6 || pn == 7 || (pn == 8 && bj == 0)) && ((wc & 1) == 0);
;                     if (ropet) {
;                         float pv[8];
; #pragma unroll
;                         for (int j = 0; j < 8; ++j) pv[j] = __shfl_xor(v[j], 16);
;                         if (fq < 2) {
;                             const f32x4* cs = (const f32x4*)(rope + (size_t)pos * 16);
;                             const float sg = (fq == 0) ? -1.f : 1.f;
; #pragma unroll
;                             for (int jj = 0; jj < 4; ++jj) { const f32x4 t = cs[jj];
;                                 v[2 * jj] = v[2 * jj] * t[0] + sg * pv[2 * jj] * t[1];
;                                 v[2 * jj + 1] = v[2 * jj + 1] * t[2] + sg * pv[2 * jj + 1] * t[3]; }
;                         }
.LBB0_906:
	s_mov_b64 s[10:11], s[20:21]
	s_mov_b64 s[58:59], s[22:23]
	s_add_u32 s8, s10, 0x43000
	s_addc_u32 s9, s11, 0
	s_cmpk_gt_i32 s66, 0x7f
	s_cselect_b64 s[6:7], -1, 0
	s_cmp_lt_i32 s14, 2
	s_cselect_b64 s[2:3], -1, 0
	s_and_b32 s12, s14, -2
	s_cmp_eq_u32 s12, 6
	s_cselect_b64 s[84:85], -1, 0
	v_mov_b32_e32 v136, v196
	s_or_b64 vcc, s[2:3], s[84:85]
	s_lshl_b32 s2, s66, 8
	s_add_i32 s2, s2, s35
	v_and_b32_e32 v173, 15, v136
	v_or_b32_e32 v144, s2, v173
	v_ashrrev_i32_e32 v145, 31, v144
	v_or_b32_e32 v154, 16, v144
	v_lshl_add_u64 v[146:147], v[144:145], 2, s[8:9]
	v_ashrrev_i32_e32 v155, 31, v154
	v_or_b32_e32 v152, 32, v144
	global_load_dword v148, v[146:147], off
	v_lshl_add_u64 v[146:147], v[154:155], 2, s[8:9]
	v_ashrrev_i32_e32 v153, 31, v152
	v_or_b32_e32 v150, 48, v144
	global_load_dword v178, v[146:147], off
	v_lshl_add_u64 v[146:147], v[152:153], 2, s[8:9]
	v_ashrrev_i32_e32 v151, 31, v150
	global_load_dword v177, v[146:147], off
	v_lshl_add_u64 v[146:147], v[150:151], 2, s[8:9]
	global_load_dword v176, v[146:147], off
	v_add_u32_e32 v146, 0x80, v144
	v_ashrrev_i32_e32 v147, 31, v146
	v_lshl_add_u64 v[146:147], v[146:147], 2, s[8:9]
	global_load_dword v174, v[146:147], off
	v_add_u32_e32 v146, 0x90, v144
	v_ashrrev_i32_e32 v147, 31, v146
	v_lshl_add_u64 v[146:147], v[146:147], 2, s[8:9]
	global_load_dword v172, v[146:147], off
	v_add_u32_e32 v146, 0xa0, v144
	v_ashrrev_i32_e32 v147, 31, v146
	v_lshl_add_u64 v[146:147], v[146:147], 2, s[8:9]
	global_load_dword v155, v[146:147], off
	v_add_u32_e32 v146, 0xb0, v144
	v_ashrrev_i32_e32 v147, 31, v146
	v_lshl_add_u64 v[146:147], v[146:147], 2, s[8:9]
	global_load_dword v153, v[146:147], off
	v_ashrrev_i32_e32 v145, 4, v136
	v_cndmask_b32_e32 v151, 1.0, v171, vcc
	v_cmp_gt_u32_e32 vcc, 16, v136
	s_add_u32 s76, s10, 0x100000
	s_addc_u32 s77, s11, 0
	s_add_i32 s3, s14, -6
	v_or_b32_e32 v175, 0x800, v173
	s_cmp_lt_u32 s3, 3
	s_cselect_b64 s[12:13], -1, 0
	s_and_b64 s[16:17], s[42:43], s[12:13]
	v_cmp_gt_i32_e64 s[8:9], 2, v145
	v_cndmask_b32_e64 v142, 1.0, -1.0, vcc
	s_andn2_b64 vcc, exec, s[16:17]
	s_waitcnt vmcnt(0)
	v_fmamk_f32 v136, v148, 0x3a800000, v170
	v_rsq_f32_e32 v136, v136
	s_nop 0
	v_mul_f32_e32 v156, v151, v136
	v_mov_b32_e32 v136, s2
	v_bitop3_b32 v157, v173, s62, v136 bitop3:0xc8
	v_cndmask_b32_e64 v136, v157, v175, s[6:7]
	v_lshlrev_b32_e32 v136, 6, v136
	v_lshl_add_u64 v[158:159], s[76:77], 0, v[136:137]
	v_cndmask_b32_e64 v136, 0, 1, s[16:17]
	v_pk_mul_f32 v[124:125], v[124:125], v[156:157] op_sel_hi:[1,0]
	v_pk_mul_f32 v[120:121], v[120:121], v[156:157] op_sel_hi:[1,0]
	v_pk_mul_f32 v[126:127], v[126:127], v[156:157] op_sel_hi:[1,0]
	v_pk_mul_f32 v[122:123], v[122:123], v[156:157] op_sel_hi:[1,0]
	v_cmp_ne_u32_e64 s[12:13], 1, v136
	s_cbranch_vccnz .LBB0_910
	v_readfirstlane_b32 s30, v158
	v_readfirstlane_b32 s31, v159
	v_mbcnt_lo_u32_b32 v236, -1, 0
	v_mbcnt_hi_u32_b32 v236, -1, v236
	v_lshlrev_b32_e32 v236, 4, v236
	s_nop 4
	s_sub_u32 s32, s30, s76
	s_bfe_u32 s32, s32, 0x1000c
	s_mul_i32 s32, s32, 0x3000
	s_add_i32 s32, s32, 0x21000
	s_add_u32 s80, s30, 0x2000
	s_addc_u32 s81, s31, 0
	global_load_dwordx4 v[204:207], v236, s[30:31]
	global_load_dwordx4 v[208:211], v236, s[30:31] offset:1024
	global_load_dwordx4 v[212:215], v236, s[30:31] offset:2048
	global_load_dwordx4 v[216:219], v236, s[30:31] offset:3072
	global_load_dwordx4 v[220:223], v236, s[80:81]
	global_load_dwordx4 v[224:227], v236, s[80:81] offset:1024
	global_load_dwordx4 v[228:231], v236, s[80:81] offset:2048
	global_load_dwordx4 v[232:235], v236, s[80:81] offset:3072
	v_add_u32_e32 v237, s32, v236
	s_sub_u32 s32, s30, s32
	s_waitcnt vmcnt(0)
	ds_write_b128 v237, v[204:207]
	ds_write_b128 v237, v[208:211] offset:1024
	ds_write_b128 v237, v[212:215] offset:2048
	ds_write_b128 v237, v[216:219] offset:3072
	ds_write_b128 v237, v[220:223] offset:8192
	ds_write_b128 v237, v[224:227] offset:9216
	ds_write_b128 v237, v[228:231] offset:10240
	ds_write_b128 v237, v[232:235] offset:11264
	s_waitcnt lgkmcnt(0)
	ds_bpermute_b32 v160, v197, v124
	ds_bpermute_b32 v161, v197, v125
	ds_bpermute_b32 v148, v197, v126
	ds_bpermute_b32 v149, v197, v127
	ds_bpermute_b32 v146, v197, v120
	ds_bpermute_b32 v147, v197, v121
	ds_bpermute_b32 v162, v197, v122
	ds_bpermute_b32 v136, v197, v123
	s_and_saveexec_b64 s[16:17], s[8:9]
	s_cbranch_execz .LBB0_909
	v_subrev_u32_e32 v240, s32, v158
	ds_read_b128 v[180:183], v240 offset:48
	ds_read_b128 v[184:187], v240 offset:32
	ds_read_b128 v[188:191], v240 offset:16
	ds_read_b128 v[192:195], v240
	s_waitcnt lgkmcnt(1)
	v_mul_f32_e32 v162, v142, v162
	v_pk_mul_f32 v[160:161], v[142:143], v[160:161] op_sel_hi:[0,1]
	v_pk_mul_f32 v[148:149], v[142:143], v[148:149] op_sel_hi:[0,1]
	v_pk_mul_f32 v[146:147], v[142:143], v[146:147] op_sel_hi:[0,1]
	s_waitcnt lgkmcnt(0)
	v_mul_f32_e32 v122, v122, v180
	v_mul_f32_e32 v162, v162, v181
	v_mov_b32_e32 v164, v192
	v_mov_b32_e32 v165, v194
	v_pk_mul_f32 v[124:125], v[124:125], v[164:165]
	v_mov_b32_e32 v164, v188
	v_mov_b32_e32 v165, v190
	v_pk_mul_f32 v[126:127], v[126:127], v[164:165]
	v_mov_b32_e32 v164, v184
	v_mov_b32_e32 v165, v186
	v_pk_mul_f32 v[120:121], v[120:121], v[164:165]
	s_waitcnt lgkmcnt(0)
	v_mul_f32_e32 v165, v142, v136
	v_mov_b32_e32 v164, v123
	v_pk_mul_f32 v[164:165], v[164:165], v[182:183]
	v_mov_b32_e32 v194, v193
	v_mov_b32_e32 v190, v189
	v_mov_b32_e32 v186, v185
	v_mov_b32_e32 v123, v165
	v_mov_b32_e32 v163, v164
	v_pk_fma_f32 v[124:125], v[160:161], v[194:195], v[124:125]
	v_pk_fma_f32 v[126:127], v[148:149], v[190:191], v[126:127]
	v_pk_fma_f32 v[120:121], v[146:147], v[186:187], v[120:121]
	v_pk_add_f32 v[122:123], v[122:123], v[162:163]

;     __device__ __forceinline__ void operator()(AccRef acc, const pg8::Unit& u, int wr, int wc, int, int) const {
;     ...
;                 const int row = pm * 256 + ai * 128 + wr * 64 + m * 16 + fr;
;                 const float rstd = __builtin_amdgcn_rsqf(sq[ai][m] * (1.0f / DM) + EPS) * (isq ? QSCALE : 1.0f);
;                 const int pos = samp ? 2048 + ((row - MP) & 63) : (row & 16383);
; #pragma unroll
;                 for (int bj = 0; bj < 2; ++bj) {
;                     const int c0 = pn * 256 + bj * 128 + wc * 32 + 8 * fq;
;                     float v[8];
; #pragma unroll
;                     for (int j = 0; j < 4; ++j) { v[j] = acc[ai][bj][m][0][j] * rstd; v[4 + j] = acc[ai][bj][m][1][j] * rstd; }
;                     const bool ropet = (pn == 6 || pn == 7 || (pn == 8 && bj == 0)) && ((wc & 1) == 0);
;                     if (ropet) {
;                         float pv[8];
; #pragma unroll
;                         for (int j = 0; j < 8; ++j) pv[j] = __shfl_xor(v[j], 16);
;                         if (fq < 2) {
;                             const f32x4* cs = (const f32x4*)(rope + (size_t)pos * 16);
;                             const float sg = (fq == 0) ? -1.f : 1.f;
; #pragma unroll
;                             for (int jj = 0; jj < 4; ++jj) { const f32x4 t = cs[jj];
;                                 v[2 * jj] = v[2 * jj] * t[0] + sg * pv[2 * jj] * t[1];
;                                 v[2 * jj + 1] = v[2 * jj + 1] * t[2] + sg * pv[2 * jj + 1] * t[3]; }
;                         }
.LBB0_914:
	s_and_b64 s[84:85], s[42:43], s[84:85]
	v_mov_b32_e32 v157, v156
	v_cndmask_b32_e64 v120, 0, 1, s[84:85]
	v_pk_mul_f32 v[116:117], v[116:117], v[156:157]
	v_pk_mul_f32 v[112:113], v[112:113], v[156:157]
	v_pk_mul_f32 v[118:119], v[118:119], v[156:157]
	v_cmp_ne_u32_e64 s[14:15], 1, v120
	s_andn2_b64 vcc, exec, s[84:85]
	v_pk_mul_f32 v[114:115], v[114:115], v[156:157]
	s_cbranch_vccnz .LBB0_918
	ds_bpermute_b32 v124, v197, v116
	ds_bpermute_b32 v125, v197, v117
	ds_bpermute_b32 v122, v197, v118
	ds_bpermute_b32 v123, v197, v119
	ds_bpermute_b32 v120, v197, v112
	ds_bpermute_b32 v121, v197, v113
	ds_bpermute_b32 v127, v197, v114
	ds_bpermute_b32 v126, v197, v115
	s_and_saveexec_b64 s[84:85], s[8:9]
	s_cbranch_execz .LBB0_917
	v_subrev_u32_e32 v240, s32, v158
	ds_read_b128 v[180:183], v240 offset:48
	ds_read_b128 v[184:187], v240 offset:32
	ds_read_b128 v[188:191], v240 offset:16
	s_nop 0
	ds_read_b128 v[156:159], v240
	s_waitcnt lgkmcnt(1)
	v_mul_f32_e32 v127, v142, v127
	v_pk_mul_f32 v[124:125], v[142:143], v[124:125] op_sel_hi:[0,1]
	v_pk_mul_f32 v[122:123], v[142:143], v[122:123] op_sel_hi:[0,1]
	v_pk_mul_f32 v[120:121], v[142:143], v[120:121] op_sel_hi:[0,1]
	s_waitcnt lgkmcnt(0)
	v_mul_f32_e32 v114, v114, v180
	v_mov_b32_e32 v192, v156
	v_mov_b32_e32 v193, v158
	v_mov_b32_e32 v158, v157
	v_mov_b32_e32 v156, v188
	v_mov_b32_e32 v157, v190
	v_pk_mul_f32 v[118:119], v[118:119], v[156:157]
	v_mov_b32_e32 v156, v184
	v_mov_b32_e32 v157, v186
	v_pk_mul_f32 v[112:113], v[112:113], v[156:157]
	v_mul_f32_e32 v156, v127, v181
	s_waitcnt lgkmcnt(0)
	v_mul_f32_e32 v127, v142, v126
	v_mov_b32_e32 v126, v115
	v_pk_mul_f32 v[126:127], v[126:127], v[182:183]
	v_pk_mul_f32 v[116:117], v[116:117], v[192:193]
	v_mov_b32_e32 v190, v189
	v_mov_b32_e32 v186, v185
	v_mov_b32_e32 v115, v127
	v_mov_b32_e32 v157, v126
	v_pk_fma_f32 v[116:117], v[124:125], v[158:159], v[116:117]
	v_pk_fma_f32 v[118:119], v[122:123], v[190:191], v[118:119]
	v_pk_fma_f32 v[112:113], v[120:121], v[186:187], v[112:113]
	v_pk_add_f32 v[114:115], v[114:115], v[156:157]

;     __device__ __forceinline__ void operator()(AccRef acc, const pg8::Unit& u, int wr, int wc, int, int) const {
;     ...
;                 const int row = pm * 256 + ai * 128 + wr * 64 + m * 16 + fr;
;                 const float rstd = __builtin_amdgcn_rsqf(sq[ai][m] * (1.0f / DM) + EPS) * (isq ? QSCALE : 1.0f);
;                 const int pos = samp ? 2048 + ((row - MP) & 63) : (row & 16383);
; #pragma unroll
;                 for (int bj = 0; bj < 2; ++bj) {
;                     const int c0 = pn * 256 + bj * 128 + wc * 32 + 8 * fq;
;                     float v[8];
; #pragma unroll
;                     for (int j = 0; j < 4; ++j) { v[j] = acc[ai][bj][m][0][j] * rstd; v[4 + j] = acc[ai][bj][m][1][j] * rstd; }
;                     const bool ropet = (pn == 6 || pn == 7 || (pn == 8 && bj == 0)) && ((wc & 1) == 0);
;                     if (ropet) {
;                         float pv[8];
; #pragma unroll
;                         for (int j = 0; j < 8; ++j) pv[j] = __shfl_xor(v[j], 16);
;                         if (fq < 2) {
;                             const f32x4* cs = (const f32x4*)(rope + (size_t)pos * 16);
;                             const float sg = (fq == 0) ? -1.f : 1.f;
; #pragma unroll
;                             for (int jj = 0; jj < 4; ++jj) { const f32x4 t = cs[jj];
;                                 v[2 * jj] = v[2 * jj] * t[0] + sg * pv[2 * jj] * t[1];
;                                 v[2 * jj + 1] = v[2 * jj + 1] * t[2] + sg * pv[2 * jj + 1] * t[3]; }
;                         }
.LBB0_922:
	s_nop 1
	v_fmamk_f32 v112, v178, 0x3a800000, v170
	v_rsq_f32_e32 v112, v112
	v_or_b32_e32 v125, 0x810, v173
	v_and_b32_e32 v115, 0x3fdf, v154
	v_cndmask_b32_e64 v113, v115, v125, s[6:7]
	v_mul_f32_e32 v114, v151, v112
	v_lshlrev_b32_e32 v136, 6, v113
	v_lshl_add_u64 v[112:113], s[76:77], 0, v[136:137]
	v_pk_mul_f32 v[108:109], v[108:109], v[114:115] op_sel_hi:[1,0]
	v_pk_mul_f32 v[104:105], v[104:105], v[114:115] op_sel_hi:[1,0]
	v_pk_mul_f32 v[110:111], v[110:111], v[114:115] op_sel_hi:[1,0]
	s_and_b64 vcc, exec, s[12:13]
	v_pk_mul_f32 v[106:107], v[106:107], v[114:115] op_sel_hi:[1,0]
	s_cbranch_vccnz .LBB0_926
	ds_bpermute_b32 v122, v197, v108
	ds_bpermute_b32 v123, v197, v109
	ds_bpermute_b32 v118, v197, v110
	ds_bpermute_b32 v119, v197, v111
	ds_bpermute_b32 v116, v197, v104
	ds_bpermute_b32 v117, v197, v105
	s_waitcnt lgkmcnt(6)
	ds_bpermute_b32 v126, v197, v106
	ds_bpermute_b32 v124, v197, v107
	s_and_saveexec_b64 s[84:85], s[8:9]
	s_cbranch_execz .LBB0_925
	v_subrev_u32_e32 v240, s32, v112
	ds_read_b128 v[156:159], v240 offset:48
	ds_read_b128 v[160:163], v240 offset:32
	ds_read_b128 v[178:181], v240 offset:16
	ds_read_b128 v[182:185], v240
	s_waitcnt lgkmcnt(1)
	v_mul_f32_e32 v126, v142, v126
	v_pk_mul_f32 v[122:123], v[142:143], v[122:123] op_sel_hi:[0,1]
	v_pk_mul_f32 v[118:119], v[142:143], v[118:119] op_sel_hi:[0,1]
	v_pk_mul_f32 v[116:117], v[142:143], v[116:117] op_sel_hi:[0,1]
	s_waitcnt lgkmcnt(0)
	v_mul_f32_e32 v106, v106, v156
	v_mul_f32_e32 v126, v126, v157
	s_waitcnt lgkmcnt(0)
	v_mul_f32_e32 v157, v142, v124
	v_mov_b32_e32 v164, v182
	v_mov_b32_e32 v165, v184
	v_pk_mul_f32 v[108:109], v[108:109], v[164:165]
	v_mov_b32_e32 v164, v178
	v_mov_b32_e32 v165, v180
	v_mov_b32_e32 v156, v107
	v_pk_mul_f32 v[110:111], v[110:111], v[164:165]
	v_mov_b32_e32 v164, v160
	v_mov_b32_e32 v165, v162
	v_pk_mul_f32 v[156:157], v[156:157], v[158:159]
	v_mov_b32_e32 v184, v183
	v_mov_b32_e32 v180, v179
	v_pk_mul_f32 v[104:105], v[104:105], v[164:165]
	v_mov_b32_e32 v162, v161
	v_mov_b32_e32 v107, v157
	v_mov_b32_e32 v127, v156
	v_pk_fma_f32 v[108:109], v[122:123], v[184:185], v[108:109]
	v_pk_fma_f32 v[110:111], v[118:119], v[180:181], v[110:111]
	v_pk_fma_f32 v[104:105], v[116:117], v[162:163], v[104:105]
	v_pk_add_f32 v[106:107], v[106:107], v[126:127]

;     __device__ __forceinline__ void operator()(AccRef acc, const pg8::Unit& u, int wr, int wc, int, int) const {
;     ...
;                 const int row = pm * 256 + ai * 128 + wr * 64 + m * 16 + fr;
;                 const float rstd = __builtin_amdgcn_rsqf(sq[ai][m] * (1.0f / DM) + EPS) * (isq ? QSCALE : 1.0f);
;                 const int pos = samp ? 2048 + ((row - MP) & 63) : (row & 16383);
; #pragma unroll
;                 for (int bj = 0; bj < 2; ++bj) {
;                     const int c0 = pn * 256 + bj * 128 + wc * 32 + 8 * fq;
;                     float v[8];
; #pragma unroll
;                     for (int j = 0; j < 4; ++j) { v[j] = acc[ai][bj][m][0][j] * rstd; v[4 + j] = acc[ai][bj][m][1][j] * rstd; }
;                     const bool ropet = (pn == 6 || pn == 7 || (pn == 8 && bj == 0)) && ((wc & 1) == 0);
;                     if (ropet) {
;                         float pv[8];
; #pragma unroll
;                         for (int j = 0; j < 8; ++j) pv[j] = __shfl_xor(v[j], 16);
;                         if (fq < 2) {
;                             const f32x4* cs = (const f32x4*)(rope + (size_t)pos * 16);
;                             const float sg = (fq == 0) ? -1.f : 1.f;
; #pragma unroll
;                             for (int jj = 0; jj < 4; ++jj) { const f32x4 t = cs[jj];
;                                 v[2 * jj] = v[2 * jj] * t[0] + sg * pv[2 * jj] * t[1];
;                                 v[2 * jj + 1] = v[2 * jj + 1] * t[2] + sg * pv[2 * jj + 1] * t[3]; }
;                         }
.LBB0_930:
	v_mov_b32_e32 v115, v114
	v_pk_mul_f32 v[100:101], v[100:101], v[114:115]
	v_pk_mul_f32 v[96:97], v[96:97], v[114:115]
	v_pk_mul_f32 v[102:103], v[102:103], v[114:115]
	s_and_b64 vcc, exec, s[14:15]
	v_pk_mul_f32 v[98:99], v[98:99], v[114:115]
	s_cbranch_vccnz .LBB0_934
	ds_bpermute_b32 v108, v197, v100
	ds_bpermute_b32 v109, v197, v101
	ds_bpermute_b32 v106, v197, v102
	ds_bpermute_b32 v107, v197, v103
	ds_bpermute_b32 v104, v197, v96
	ds_bpermute_b32 v105, v197, v97
	ds_bpermute_b32 v111, v197, v98
	ds_bpermute_b32 v110, v197, v99
	s_and_saveexec_b64 s[84:85], s[8:9]
	s_cbranch_execz .LBB0_933
	v_subrev_u32_e32 v240, s32, v112
	ds_read_b128 v[156:159], v240 offset:48
	ds_read_b128 v[160:163], v240 offset:32
	ds_read_b128 v[178:181], v240 offset:16
	s_nop 0
	ds_read_b128 v[112:115], v240
	s_waitcnt lgkmcnt(1)
	v_mul_f32_e32 v111, v142, v111
	v_pk_mul_f32 v[108:109], v[142:143], v[108:109] op_sel_hi:[0,1]
	v_pk_mul_f32 v[106:107], v[142:143], v[106:107] op_sel_hi:[0,1]
	v_pk_mul_f32 v[104:105], v[142:143], v[104:105] op_sel_hi:[0,1]
	s_waitcnt lgkmcnt(0)
	v_mul_f32_e32 v98, v98, v156
	v_mov_b32_e32 v126, v112
	v_mov_b32_e32 v127, v114
	v_mov_b32_e32 v114, v113
	v_mov_b32_e32 v112, v178
	v_mov_b32_e32 v113, v180
	v_pk_mul_f32 v[102:103], v[102:103], v[112:113]
	v_mov_b32_e32 v112, v160
	v_mov_b32_e32 v113, v162
	v_pk_mul_f32 v[96:97], v[96:97], v[112:113]
	v_mul_f32_e32 v112, v111, v157
	s_waitcnt lgkmcnt(0)
	v_mul_f32_e32 v111, v142, v110
	v_mov_b32_e32 v110, v99
	v_pk_mul_f32 v[110:111], v[110:111], v[158:159]
	v_pk_mul_f32 v[100:101], v[100:101], v[126:127]
	v_mov_b32_e32 v180, v179
	v_mov_b32_e32 v162, v161
	v_mov_b32_e32 v99, v111
	v_mov_b32_e32 v113, v110
	v_pk_fma_f32 v[100:101], v[108:109], v[114:115], v[100:101]
	v_pk_fma_f32 v[102:103], v[106:107], v[180:181], v[102:103]
	v_pk_fma_f32 v[96:97], v[104:105], v[162:163], v[96:97]
	v_pk_add_f32 v[98:99], v[98:99], v[112:113]

;     __device__ __forceinline__ void operator()(AccRef acc, const pg8::Unit& u, int wr, int wc, int, int) const {
;     ...
;                 const int row = pm * 256 + ai * 128 + wr * 64 + m * 16 + fr;
;                 const float rstd = __builtin_amdgcn_rsqf(sq[ai][m] * (1.0f / DM) + EPS) * (isq ? QSCALE : 1.0f);
;                 const int pos = samp ? 2048 + ((row - MP) & 63) : (row & 16383);
; #pragma unroll
;                 for (int bj = 0; bj < 2; ++bj) {
;                     const int c0 = pn * 256 + bj * 128 + wc * 32 + 8 * fq;
;                     float v[8];
; #pragma unroll
;                     for (int j = 0; j < 4; ++j) { v[j] = acc[ai][bj][m][0][j] * rstd; v[4 + j] = acc[ai][bj][m][1][j] * rstd; }
;                     const bool ropet = (pn == 6 || pn == 7 || (pn == 8 && bj == 0)) && ((wc & 1) == 0);
;                     if (ropet) {
;                         float pv[8];
; #pragma unroll
;                         for (int j = 0; j < 8; ++j) pv[j] = __shfl_xor(v[j], 16);
;                         if (fq < 2) {
;                             const f32x4* cs = (const f32x4*)(rope + (size_t)pos * 16);
;                             const float sg = (fq == 0) ? -1.f : 1.f;
; #pragma unroll
;                             for (int jj = 0; jj < 4; ++jj) { const f32x4 t = cs[jj];
;                                 v[2 * jj] = v[2 * jj] * t[0] + sg * pv[2 * jj] * t[1];
;                                 v[2 * jj + 1] = v[2 * jj + 1] * t[2] + sg * pv[2 * jj + 1] * t[3]; }
;                         }
.LBB0_938:
	s_nop 1
	v_fmamk_f32 v96, v177, 0x3a800000, v170
	v_rsq_f32_e32 v96, v96
	v_or_b32_e32 v107, 0x820, v173
	v_and_b32_e32 v99, 0x3fef, v152
	v_cndmask_b32_e64 v97, v99, v107, s[6:7]
	v_mul_f32_e32 v98, v151, v96
	v_lshlrev_b32_e32 v136, 6, v97
	v_lshl_add_u64 v[96:97], s[76:77], 0, v[136:137]
	v_pk_mul_f32 v[92:93], v[92:93], v[98:99] op_sel_hi:[1,0]
	v_pk_mul_f32 v[88:89], v[88:89], v[98:99] op_sel_hi:[1,0]
	v_pk_mul_f32 v[94:95], v[94:95], v[98:99] op_sel_hi:[1,0]
	s_and_b64 vcc, exec, s[12:13]
	v_pk_mul_f32 v[90:91], v[90:91], v[98:99] op_sel_hi:[1,0]
	s_cbranch_vccnz .LBB0_942
	ds_bpermute_b32 v104, v197, v92
	ds_bpermute_b32 v105, v197, v93
	ds_bpermute_b32 v102, v197, v94
	ds_bpermute_b32 v103, v197, v95
	ds_bpermute_b32 v100, v197, v88
	ds_bpermute_b32 v101, v197, v89
	ds_bpermute_b32 v108, v197, v90
	ds_bpermute_b32 v106, v197, v91
	s_and_saveexec_b64 s[84:85], s[8:9]
	s_cbranch_execz .LBB0_941
	s_waitcnt lgkmcnt(8)
	v_subrev_u32_e32 v240, s32, v96
	ds_read_b128 v[110:113], v240 offset:48
	ds_read_b128 v[114:117], v240 offset:32
	ds_read_b128 v[156:159], v240 offset:16
	ds_read_b128 v[160:163], v240
	s_waitcnt lgkmcnt(1)
	v_mul_f32_e32 v108, v142, v108
	v_pk_mul_f32 v[104:105], v[142:143], v[104:105] op_sel_hi:[0,1]
	v_pk_mul_f32 v[102:103], v[142:143], v[102:103] op_sel_hi:[0,1]
	v_pk_mul_f32 v[100:101], v[142:143], v[100:101] op_sel_hi:[0,1]
	s_waitcnt lgkmcnt(0)
	v_mul_f32_e32 v90, v90, v110
	v_mul_f32_e32 v108, v108, v111
	s_waitcnt lgkmcnt(0)
	v_mul_f32_e32 v111, v142, v106
	v_mov_b32_e32 v118, v160
	v_mov_b32_e32 v119, v162
	v_pk_mul_f32 v[92:93], v[92:93], v[118:119]
	v_mov_b32_e32 v118, v156
	v_mov_b32_e32 v119, v158
	v_mov_b32_e32 v110, v91
	v_pk_mul_f32 v[94:95], v[94:95], v[118:119]
	v_mov_b32_e32 v118, v114
	v_mov_b32_e32 v119, v116
	v_pk_mul_f32 v[110:111], v[110:111], v[112:113]
	v_mov_b32_e32 v162, v161
	v_mov_b32_e32 v158, v157
	v_pk_mul_f32 v[88:89], v[88:89], v[118:119]
	v_mov_b32_e32 v116, v115
	v_mov_b32_e32 v91, v111
	v_mov_b32_e32 v109, v110
	v_pk_fma_f32 v[92:93], v[104:105], v[162:163], v[92:93]
	v_pk_fma_f32 v[94:95], v[102:103], v[158:159], v[94:95]
	v_pk_fma_f32 v[88:89], v[100:101], v[116:117], v[88:89]
	v_pk_add_f32 v[90:91], v[90:91], v[108:109]

;     __device__ __forceinline__ void operator()(AccRef acc, const pg8::Unit& u, int wr, int wc, int, int) const {
;     ...
;                     for (int j = 0; j < 4; ++j) { v[j] = acc[ai][bj][m][0][j] * rstd; v[4 + j] = acc[ai][bj][m][1][j] * rstd; }
;                     const bool ropet = (pn == 6 || pn == 7 || (pn == 8 && bj == 0)) && ((wc & 1) == 0);
;                     if (ropet) {
;                         float pv[8];
; #pragma unroll
;                         for (int j = 0; j < 8; ++j) pv[j] = __shfl_xor(v[j], 16);
;                         if (fq < 2) {
;                             const f32x4* cs = (const f32x4*)(rope + (size_t)pos * 16);
;                             const float sg = (fq == 0) ? -1.f : 1.f;
; #pragma unroll
;                             for (int jj = 0; jj < 4; ++jj) { const f32x4 t = cs[jj];
;                                 v[2 * jj] = v[2 * jj] * t[0] + sg * pv[2 * jj] * t[1];
;                                 v[2 * jj + 1] = v[2 * jj + 1] * t[2] + sg * pv[2 * jj + 1] * t[3]; }
;                         }
.LBB0_946:
	v_mov_b32_e32 v99, v98
	v_pk_mul_f32 v[84:85], v[84:85], v[98:99]
	v_pk_mul_f32 v[80:81], v[80:81], v[98:99]
	v_pk_mul_f32 v[86:87], v[86:87], v[98:99]
	s_and_b64 vcc, exec, s[14:15]
	v_pk_mul_f32 v[82:83], v[82:83], v[98:99]
	s_cbranch_vccnz .LBB0_950
	ds_bpermute_b32 v92, v197, v84
	ds_bpermute_b32 v93, v197, v85
	ds_bpermute_b32 v90, v197, v86
	ds_bpermute_b32 v91, v197, v87
	ds_bpermute_b32 v88, v197, v80
	ds_bpermute_b32 v89, v197, v81
	ds_bpermute_b32 v95, v197, v82
	ds_bpermute_b32 v94, v197, v83
	s_and_saveexec_b64 s[84:85], s[8:9]
	s_cbranch_execz .LBB0_949
	v_subrev_u32_e32 v240, s32, v96
	ds_read_b128 v[108:111], v240 offset:48
	ds_read_b128 v[112:115], v240 offset:32
	ds_read_b128 v[116:119], v240 offset:16
	s_nop 0
	ds_read_b128 v[96:99], v240
	s_waitcnt lgkmcnt(1)
	v_mul_f32_e32 v95, v142, v95
	v_pk_mul_f32 v[92:93], v[142:143], v[92:93] op_sel_hi:[0,1]
	v_pk_mul_f32 v[90:91], v[142:143], v[90:91] op_sel_hi:[0,1]
	v_pk_mul_f32 v[88:89], v[142:143], v[88:89] op_sel_hi:[0,1]
	s_waitcnt lgkmcnt(0)
	v_mul_f32_e32 v82, v82, v108
	v_mov_b32_e32 v122, v96
	v_mov_b32_e32 v123, v98
	v_mov_b32_e32 v98, v97
	v_mov_b32_e32 v96, v116
	v_mov_b32_e32 v97, v118
	v_pk_mul_f32 v[86:87], v[86:87], v[96:97]
	v_mov_b32_e32 v96, v112
	v_mov_b32_e32 v97, v114
	v_pk_mul_f32 v[80:81], v[80:81], v[96:97]
	v_mul_f32_e32 v96, v95, v109
	s_waitcnt lgkmcnt(0)
	v_mul_f32_e32 v95, v142, v94
	v_mov_b32_e32 v94, v83
	v_pk_mul_f32 v[94:95], v[94:95], v[110:111]
	v_pk_mul_f32 v[84:85], v[84:85], v[122:123]
	v_mov_b32_e32 v118, v117
	v_mov_b32_e32 v114, v113
	v_mov_b32_e32 v83, v95
	v_mov_b32_e32 v97, v94
	v_pk_fma_f32 v[84:85], v[92:93], v[98:99], v[84:85]
	v_pk_fma_f32 v[86:87], v[90:91], v[118:119], v[86:87]
	v_pk_fma_f32 v[80:81], v[88:89], v[114:115], v[80:81]
	v_pk_add_f32 v[82:83], v[82:83], v[96:97]

;     __device__ __forceinline__ void operator()(AccRef acc, const pg8::Unit& u, int wr, int wc, int, int) const {
;     ...
;                 const float rstd = __builtin_amdgcn_rsqf(sq[ai][m] * (1.0f / DM) + EPS) * (isq ? QSCALE : 1.0f);
;                 const int pos = samp ? 2048 + ((row - MP) & 63) : (row & 16383);
; #pragma unroll
;                 for (int bj = 0; bj < 2; ++bj) {
;                     const int c0 = pn * 256 + bj * 128 + wc * 32 + 8 * fq;
;                     float v[8];
; #pragma unroll
;                     for (int j = 0; j < 4; ++j) { v[j] = acc[ai][bj][m][0][j] * rstd; v[4 + j] = acc[ai][bj][m][1][j] * rstd; }
;                     const bool ropet = (pn == 6 || pn == 7 || (pn == 8 && bj == 0)) && ((wc & 1) == 0);
;                     if (ropet) {
;                         float pv[8];
; #pragma unroll
;                         for (int j = 0; j < 8; ++j) pv[j] = __shfl_xor(v[j], 16);
;                         if (fq < 2) {
;                             const f32x4* cs = (const f32x4*)(rope + (size_t)pos * 16);
;                             const float sg = (fq == 0) ? -1.f : 1.f;
; #pragma unroll
;                             for (int jj = 0; jj < 4; ++jj) { const f32x4 t = cs[jj];
;                                 v[2 * jj] = v[2 * jj] * t[0] + sg * pv[2 * jj] * t[1];
;                                 v[2 * jj + 1] = v[2 * jj + 1] * t[2] + sg * pv[2 * jj + 1] * t[3]; }
;                         }
.LBB0_954:
	s_nop 1
	v_fmamk_f32 v80, v176, 0x3a800000, v170
	v_rsq_f32_e32 v80, v80
	v_or_b32_e32 v91, 0x830, v173
	v_and_b32_e32 v83, 0x3fff, v150
	v_cndmask_b32_e64 v81, v83, v91, s[6:7]
	v_mul_f32_e32 v82, v151, v80
	v_lshlrev_b32_e32 v136, 6, v81
	v_lshl_add_u64 v[80:81], s[76:77], 0, v[136:137]
	v_pk_mul_f32 v[76:77], v[76:77], v[82:83] op_sel_hi:[1,0]
	v_pk_mul_f32 v[72:73], v[72:73], v[82:83] op_sel_hi:[1,0]
	v_pk_mul_f32 v[78:79], v[78:79], v[82:83] op_sel_hi:[1,0]
	s_and_b64 vcc, exec, s[12:13]
	v_pk_mul_f32 v[74:75], v[74:75], v[82:83] op_sel_hi:[1,0]
	s_cbranch_vccnz .LBB0_958
	ds_bpermute_b32 v88, v197, v76
	ds_bpermute_b32 v89, v197, v77
	ds_bpermute_b32 v86, v197, v78
	ds_bpermute_b32 v87, v197, v79
	ds_bpermute_b32 v84, v197, v72
	ds_bpermute_b32 v85, v197, v73
	ds_bpermute_b32 v92, v197, v74
	ds_bpermute_b32 v90, v197, v75
	s_and_saveexec_b64 s[84:85], s[8:9]
	s_cbranch_execz .LBB0_957
	s_waitcnt lgkmcnt(8)
	v_subrev_u32_e32 v240, s32, v80
	ds_read_b128 v[94:97], v240 offset:48
	ds_read_b128 v[98:101], v240 offset:32
	ds_read_b128 v[102:105], v240 offset:16
	ds_read_b128 v[108:111], v240
	s_waitcnt lgkmcnt(1)
	v_mul_f32_e32 v92, v142, v92
	v_pk_mul_f32 v[88:89], v[142:143], v[88:89] op_sel_hi:[0,1]
	v_pk_mul_f32 v[86:87], v[142:143], v[86:87] op_sel_hi:[0,1]
	v_pk_mul_f32 v[84:85], v[142:143], v[84:85] op_sel_hi:[0,1]
	s_waitcnt lgkmcnt(0)
	v_mul_f32_e32 v74, v74, v94
	v_mul_f32_e32 v92, v92, v95
	s_waitcnt lgkmcnt(0)
	v_mul_f32_e32 v95, v142, v90
	v_mov_b32_e32 v94, v75
	v_mov_b32_e32 v112, v108
	v_mov_b32_e32 v113, v110
	v_mov_b32_e32 v110, v109
	v_mov_b32_e32 v108, v102
	v_mov_b32_e32 v109, v104
	v_mov_b32_e32 v104, v103
	v_mov_b32_e32 v102, v98
	v_mov_b32_e32 v103, v100
	v_pk_mul_f32 v[94:95], v[94:95], v[96:97]
	v_pk_mul_f32 v[76:77], v[76:77], v[112:113]
	v_pk_mul_f32 v[78:79], v[78:79], v[108:109]
	v_pk_mul_f32 v[72:73], v[72:73], v[102:103]
	v_mov_b32_e32 v100, v99
	v_mov_b32_e32 v75, v95
	v_mov_b32_e32 v93, v94
	v_pk_fma_f32 v[76:77], v[88:89], v[110:111], v[76:77]
	v_pk_fma_f32 v[78:79], v[86:87], v[104:105], v[78:79]
	v_pk_fma_f32 v[72:73], v[84:85], v[100:101], v[72:73]
	v_pk_add_f32 v[74:75], v[74:75], v[92:93]

;     __device__ __forceinline__ void operator()(AccRef acc, const pg8::Unit& u, int wr, int wc, int, int) const {
;     ...
;                     for (int j = 0; j < 4; ++j) { v[j] = acc[ai][bj][m][0][j] * rstd; v[4 + j] = acc[ai][bj][m][1][j] * rstd; }
;                     const bool ropet = (pn == 6 || pn == 7 || (pn == 8 && bj == 0)) && ((wc & 1) == 0);
;                     if (ropet) {
;                         float pv[8];
; #pragma unroll
;                         for (int j = 0; j < 8; ++j) pv[j] = __shfl_xor(v[j], 16);
;                         if (fq < 2) {
;                             const f32x4* cs = (const f32x4*)(rope + (size_t)pos * 16);
;                             const float sg = (fq == 0) ? -1.f : 1.f;
; #pragma unroll
;                             for (int jj = 0; jj < 4; ++jj) { const f32x4 t = cs[jj];
;                                 v[2 * jj] = v[2 * jj] * t[0] + sg * pv[2 * jj] * t[1];
;                                 v[2 * jj + 1] = v[2 * jj + 1] * t[2] + sg * pv[2 * jj + 1] * t[3]; }
;                         }
.LBB0_962:
	v_mov_b32_e32 v83, v82
	v_pk_mul_f32 v[68:69], v[68:69], v[82:83]
	v_pk_mul_f32 v[64:65], v[64:65], v[82:83]
	v_pk_mul_f32 v[70:71], v[70:71], v[82:83]
	s_and_b64 vcc, exec, s[14:15]
	v_pk_mul_f32 v[66:67], v[66:67], v[82:83]
	s_cbranch_vccnz .LBB0_966
	ds_bpermute_b32 v76, v197, v68
	ds_bpermute_b32 v77, v197, v69
	ds_bpermute_b32 v74, v197, v70
	ds_bpermute_b32 v75, v197, v71
	ds_bpermute_b32 v72, v197, v64
	ds_bpermute_b32 v73, v197, v65
	ds_bpermute_b32 v79, v197, v66
	ds_bpermute_b32 v78, v197, v67
	s_and_saveexec_b64 s[84:85], s[8:9]
	s_cbranch_execz .LBB0_965
	v_subrev_u32_e32 v240, s32, v80
	ds_read_b128 v[92:95], v240 offset:48
	ds_read_b128 v[96:99], v240 offset:32
	ds_read_b128 v[100:103], v240 offset:16
	s_nop 0
	ds_read_b128 v[80:83], v240
	s_waitcnt lgkmcnt(1)
	v_mul_f32_e32 v79, v142, v79
	v_pk_mul_f32 v[76:77], v[142:143], v[76:77] op_sel_hi:[0,1]
	v_pk_mul_f32 v[74:75], v[142:143], v[74:75] op_sel_hi:[0,1]
	v_pk_mul_f32 v[72:73], v[142:143], v[72:73] op_sel_hi:[0,1]
	s_waitcnt lgkmcnt(0)
	v_mul_f32_e32 v66, v66, v92
	v_mov_b32_e32 v104, v80
	v_mov_b32_e32 v105, v82
	v_mov_b32_e32 v82, v81
	v_mov_b32_e32 v80, v100
	v_mov_b32_e32 v81, v102
	v_pk_mul_f32 v[70:71], v[70:71], v[80:81]
	v_mov_b32_e32 v80, v96
	v_mov_b32_e32 v81, v98
	v_pk_mul_f32 v[64:65], v[64:65], v[80:81]
	v_mul_f32_e32 v80, v79, v93
	s_waitcnt lgkmcnt(0)
	v_mul_f32_e32 v79, v142, v78
	v_mov_b32_e32 v78, v67
	v_pk_mul_f32 v[78:79], v[78:79], v[94:95]
	v_pk_mul_f32 v[68:69], v[68:69], v[104:105]
	v_mov_b32_e32 v102, v101
	v_mov_b32_e32 v98, v97
	v_mov_b32_e32 v67, v79
	v_mov_b32_e32 v81, v78
	v_pk_fma_f32 v[68:69], v[76:77], v[82:83], v[68:69]
	v_pk_fma_f32 v[70:71], v[74:75], v[102:103], v[70:71]
	v_pk_fma_f32 v[64:65], v[72:73], v[98:99], v[64:65]
	v_pk_add_f32 v[66:67], v[66:67], v[80:81]

;     __device__ __forceinline__ void operator()(AccRef acc, const pg8::Unit& u, int wr, int wc, int, int) const {
;     ...
;                 const float rstd = __builtin_amdgcn_rsqf(sq[ai][m] * (1.0f / DM) + EPS) * (isq ? QSCALE : 1.0f);
;                 const int pos = samp ? 2048 + ((row - MP) & 63) : (row & 16383);
; #pragma unroll
;                 for (int bj = 0; bj < 2; ++bj) {
;                     const int c0 = pn * 256 + bj * 128 + wc * 32 + 8 * fq;
;                     float v[8];
; #pragma unroll
;                     for (int j = 0; j < 4; ++j) { v[j] = acc[ai][bj][m][0][j] * rstd; v[4 + j] = acc[ai][bj][m][1][j] * rstd; }
;                     const bool ropet = (pn == 6 || pn == 7 || (pn == 8 && bj == 0)) && ((wc & 1) == 0);
;                     if (ropet) {
;                         float pv[8];
; #pragma unroll
;                         for (int j = 0; j < 8; ++j) pv[j] = __shfl_xor(v[j], 16);
;                         if (fq < 2) {
;                             const f32x4* cs = (const f32x4*)(rope + (size_t)pos * 16);
;                             const float sg = (fq == 0) ? -1.f : 1.f;
; #pragma unroll
;                             for (int jj = 0; jj < 4; ++jj) { const f32x4 t = cs[jj];
;                                 v[2 * jj] = v[2 * jj] * t[0] + sg * pv[2 * jj] * t[1];
;                                 v[2 * jj + 1] = v[2 * jj + 1] * t[2] + sg * pv[2 * jj + 1] * t[3]; }
;                         }
.LBB0_970:
	s_nop 1
	v_fmamk_f32 v64, v174, 0x3a800000, v170
	v_rsq_f32_e32 v64, v64
	s_add_i32 s49, s2, 0x80
	v_mov_b32_e32 v65, s49
	v_bitop3_b32 v67, v173, s62, v65 bitop3:0xc8
	v_mul_f32_e32 v66, v151, v64
	v_cndmask_b32_e64 v64, v67, v175, s[6:7]
	v_lshlrev_b32_e32 v136, 6, v64
	v_lshl_add_u64 v[64:65], s[76:77], 0, v[136:137]
	v_pk_mul_f32 v[60:61], v[60:61], v[66:67] op_sel_hi:[1,0]
	v_pk_mul_f32 v[56:57], v[56:57], v[66:67] op_sel_hi:[1,0]
	v_pk_mul_f32 v[62:63], v[62:63], v[66:67] op_sel_hi:[1,0]
	s_and_b64 vcc, exec, s[12:13]
	v_pk_mul_f32 v[58:59], v[58:59], v[66:67] op_sel_hi:[1,0]
	s_cbranch_vccnz .LBB0_974
	ds_bpermute_b32 v72, v197, v60
	ds_bpermute_b32 v73, v197, v61
	ds_bpermute_b32 v70, v197, v62
	ds_bpermute_b32 v71, v197, v63
	ds_bpermute_b32 v68, v197, v56
	ds_bpermute_b32 v69, v197, v57
	ds_bpermute_b32 v75, v197, v58
	ds_bpermute_b32 v74, v197, v59
	s_and_saveexec_b64 s[16:17], s[8:9]
	s_cbranch_execz .LBB0_973
	s_waitcnt lgkmcnt(8)
	v_subrev_u32_e32 v240, s32, v64
	ds_read_b128 v[76:79], v240 offset:48
	ds_read_b128 v[80:83], v240 offset:32
	ds_read_b128 v[84:87], v240 offset:16
	ds_read_b128 v[92:95], v240
	s_waitcnt lgkmcnt(1)
	v_mul_f32_e32 v75, v142, v75
	v_pk_mul_f32 v[72:73], v[142:143], v[72:73] op_sel_hi:[0,1]
	v_pk_mul_f32 v[70:71], v[142:143], v[70:71] op_sel_hi:[0,1]
	v_pk_mul_f32 v[68:69], v[142:143], v[68:69] op_sel_hi:[0,1]
	s_waitcnt lgkmcnt(0)
	v_mul_f32_e32 v58, v58, v76
	v_mul_f32_e32 v76, v75, v77
	s_waitcnt lgkmcnt(0)
	v_mul_f32_e32 v75, v142, v74
	v_mov_b32_e32 v88, v92
	v_mov_b32_e32 v89, v94
	v_mov_b32_e32 v74, v59
	v_pk_mul_f32 v[60:61], v[60:61], v[88:89]
	v_mov_b32_e32 v88, v84
	v_mov_b32_e32 v89, v86
	v_mov_b32_e32 v86, v85
	v_mov_b32_e32 v84, v80
	v_mov_b32_e32 v85, v82
	v_pk_mul_f32 v[74:75], v[74:75], v[78:79]
	v_mov_b32_e32 v94, v93
	v_pk_mul_f32 v[62:63], v[62:63], v[88:89]
	v_pk_mul_f32 v[56:57], v[56:57], v[84:85]
	v_mov_b32_e32 v82, v81
	v_mov_b32_e32 v59, v75
	v_mov_b32_e32 v77, v74
	v_pk_fma_f32 v[60:61], v[72:73], v[94:95], v[60:61]
	v_pk_fma_f32 v[62:63], v[70:71], v[86:87], v[62:63]
	v_pk_fma_f32 v[56:57], v[68:69], v[82:83], v[56:57]
	v_pk_add_f32 v[58:59], v[58:59], v[76:77]

;     __device__ __forceinline__ void operator()(AccRef acc, const pg8::Unit& u, int wr, int wc, int, int) const {
;     ...
;                     for (int j = 0; j < 4; ++j) { v[j] = acc[ai][bj][m][0][j] * rstd; v[4 + j] = acc[ai][bj][m][1][j] * rstd; }
;                     const bool ropet = (pn == 6 || pn == 7 || (pn == 8 && bj == 0)) && ((wc & 1) == 0);
;                     if (ropet) {
;                         float pv[8];
; #pragma unroll
;                         for (int j = 0; j < 8; ++j) pv[j] = __shfl_xor(v[j], 16);
;                         if (fq < 2) {
;                             const f32x4* cs = (const f32x4*)(rope + (size_t)pos * 16);
;                             const float sg = (fq == 0) ? -1.f : 1.f;
; #pragma unroll
;                             for (int jj = 0; jj < 4; ++jj) { const f32x4 t = cs[jj];
;                                 v[2 * jj] = v[2 * jj] * t[0] + sg * pv[2 * jj] * t[1];
;                                 v[2 * jj + 1] = v[2 * jj + 1] * t[2] + sg * pv[2 * jj + 1] * t[3]; }
;                         }
.LBB0_978:
	v_mov_b32_e32 v67, v66
	v_pk_mul_f32 v[52:53], v[52:53], v[66:67]
	v_pk_mul_f32 v[48:49], v[48:49], v[66:67]
	v_pk_mul_f32 v[54:55], v[54:55], v[66:67]
	s_and_b64 vcc, exec, s[14:15]
	v_pk_mul_f32 v[50:51], v[50:51], v[66:67]
	s_cbranch_vccnz .LBB0_982
	ds_bpermute_b32 v60, v197, v52
	ds_bpermute_b32 v61, v197, v53
	ds_bpermute_b32 v58, v197, v54
	ds_bpermute_b32 v59, v197, v55
	ds_bpermute_b32 v56, v197, v48
	ds_bpermute_b32 v57, v197, v49
	ds_bpermute_b32 v63, v197, v50
	ds_bpermute_b32 v62, v197, v51
	s_and_saveexec_b64 s[30:31], s[8:9]
	s_cbranch_execz .LBB0_981
	v_subrev_u32_e32 v240, s32, v64
	ds_read_b128 v[76:79], v240 offset:48
	ds_read_b128 v[80:83], v240 offset:32
	ds_read_b128 v[84:87], v240 offset:16
	s_nop 0
	ds_read_b128 v[64:67], v240
	s_waitcnt lgkmcnt(1)
	v_mul_f32_e32 v63, v142, v63
	v_pk_mul_f32 v[60:61], v[142:143], v[60:61] op_sel_hi:[0,1]
	v_pk_mul_f32 v[58:59], v[142:143], v[58:59] op_sel_hi:[0,1]
	v_pk_mul_f32 v[56:57], v[142:143], v[56:57] op_sel_hi:[0,1]
	s_waitcnt lgkmcnt(0)
	v_mul_f32_e32 v50, v50, v76
	v_mov_b32_e32 v88, v64
	v_mov_b32_e32 v89, v66
	v_mov_b32_e32 v66, v65
	v_mov_b32_e32 v64, v84
	v_mov_b32_e32 v65, v86
	v_pk_mul_f32 v[54:55], v[54:55], v[64:65]
	v_mov_b32_e32 v64, v80
	v_mov_b32_e32 v65, v82
	v_pk_mul_f32 v[48:49], v[48:49], v[64:65]
	v_mul_f32_e32 v64, v63, v77
	s_waitcnt lgkmcnt(0)
	v_mul_f32_e32 v63, v142, v62
	v_mov_b32_e32 v62, v51
	v_pk_mul_f32 v[62:63], v[62:63], v[78:79]
	v_pk_mul_f32 v[52:53], v[52:53], v[88:89]
	v_mov_b32_e32 v86, v85
	v_mov_b32_e32 v82, v81
	v_mov_b32_e32 v51, v63
	v_mov_b32_e32 v65, v62
	v_pk_fma_f32 v[52:53], v[60:61], v[66:67], v[52:53]
	v_pk_fma_f32 v[54:55], v[58:59], v[86:87], v[54:55]
	v_pk_fma_f32 v[48:49], v[56:57], v[82:83], v[48:49]
	v_pk_add_f32 v[50:51], v[50:51], v[64:65]

;     __device__ __forceinline__ void operator()(AccRef acc, const pg8::Unit& u, int wr, int wc, int, int) const {
;     ...
;                 const float rstd = __builtin_amdgcn_rsqf(sq[ai][m] * (1.0f / DM) + EPS) * (isq ? QSCALE : 1.0f);
;                 const int pos = samp ? 2048 + ((row - MP) & 63) : (row & 16383);
; #pragma unroll
;                 for (int bj = 0; bj < 2; ++bj) {
;                     const int c0 = pn * 256 + bj * 128 + wc * 32 + 8 * fq;
;                     float v[8];
; #pragma unroll
;                     for (int j = 0; j < 4; ++j) { v[j] = acc[ai][bj][m][0][j] * rstd; v[4 + j] = acc[ai][bj][m][1][j] * rstd; }
;                     const bool ropet = (pn == 6 || pn == 7 || (pn == 8 && bj == 0)) && ((wc & 1) == 0);
;                     if (ropet) {
;                         float pv[8];
; #pragma unroll
;                         for (int j = 0; j < 8; ++j) pv[j] = __shfl_xor(v[j], 16);
;                         if (fq < 2) {
;                             const f32x4* cs = (const f32x4*)(rope + (size_t)pos * 16);
;                             const float sg = (fq == 0) ? -1.f : 1.f;
; #pragma unroll
;                             for (int jj = 0; jj < 4; ++jj) { const f32x4 t = cs[jj];
;                                 v[2 * jj] = v[2 * jj] * t[0] + sg * pv[2 * jj] * t[1];
;                                 v[2 * jj + 1] = v[2 * jj + 1] * t[2] + sg * pv[2 * jj + 1] * t[3]; }
;                         }
.LBB0_986:
	s_nop 1
	v_fmamk_f32 v48, v172, 0x3a800000, v170
	v_rsq_f32_e32 v48, v48
	s_movk_i32 s30, 0x3fdf
	v_bitop3_b32 v51, v74, s30, 16 bitop3:0xc8
	v_cndmask_b32_e64 v49, v51, v125, s[6:7]
	v_lshlrev_b32_e32 v136, 6, v49
	v_mul_f32_e32 v50, v151, v48
	v_lshl_add_u64 v[48:49], s[76:77], 0, v[136:137]
	v_pk_mul_f32 v[44:45], v[44:45], v[50:51] op_sel_hi:[1,0]
	v_pk_mul_f32 v[40:41], v[40:41], v[50:51] op_sel_hi:[1,0]
	v_pk_mul_f32 v[46:47], v[46:47], v[50:51] op_sel_hi:[1,0]
	s_and_b64 vcc, exec, s[12:13]
	v_pk_mul_f32 v[42:43], v[42:43], v[50:51] op_sel_hi:[1,0]
	s_cbranch_vccnz .LBB0_990
	ds_bpermute_b32 v56, v197, v44
	ds_bpermute_b32 v57, v197, v45
	ds_bpermute_b32 v54, v197, v46
	ds_bpermute_b32 v55, v197, v47
	ds_bpermute_b32 v52, v197, v40
	ds_bpermute_b32 v53, v197, v41
	ds_bpermute_b32 v59, v197, v42
	ds_bpermute_b32 v58, v197, v43
	s_and_saveexec_b64 s[30:31], s[8:9]
	s_cbranch_execz .LBB0_989
	s_waitcnt lgkmcnt(8)
	v_subrev_u32_e32 v240, s32, v48
	ds_read_b128 v[60:63], v240 offset:48
	ds_read_b128 v[64:67], v240 offset:32
	ds_read_b128 v[68:71], v240 offset:16
	ds_read_b128 v[76:79], v240
	s_waitcnt lgkmcnt(1)
	v_mul_f32_e32 v59, v142, v59
	v_pk_mul_f32 v[56:57], v[142:143], v[56:57] op_sel_hi:[0,1]
	v_pk_mul_f32 v[54:55], v[142:143], v[54:55] op_sel_hi:[0,1]
	v_pk_mul_f32 v[52:53], v[142:143], v[52:53] op_sel_hi:[0,1]
	s_waitcnt lgkmcnt(0)
	v_mul_f32_e32 v42, v42, v60
	v_mul_f32_e32 v60, v59, v61
	s_waitcnt lgkmcnt(0)
	v_mul_f32_e32 v59, v142, v58
	v_mov_b32_e32 v72, v76
	v_mov_b32_e32 v73, v78
	v_mov_b32_e32 v58, v43
	v_pk_mul_f32 v[44:45], v[44:45], v[72:73]
	v_mov_b32_e32 v72, v68
	v_mov_b32_e32 v73, v70
	v_mov_b32_e32 v70, v69
	v_mov_b32_e32 v68, v64
	v_mov_b32_e32 v69, v66
	v_pk_mul_f32 v[58:59], v[58:59], v[62:63]
	v_mov_b32_e32 v78, v77
	v_pk_mul_f32 v[46:47], v[46:47], v[72:73]
	v_pk_mul_f32 v[40:41], v[40:41], v[68:69]
	v_mov_b32_e32 v66, v65
	v_mov_b32_e32 v43, v59
	v_mov_b32_e32 v61, v58
	v_pk_fma_f32 v[44:45], v[56:57], v[78:79], v[44:45]
	v_pk_fma_f32 v[46:47], v[54:55], v[70:71], v[46:47]
	v_pk_fma_f32 v[40:41], v[52:53], v[66:67], v[40:41]
	v_pk_add_f32 v[42:43], v[42:43], v[60:61]

;     __device__ __forceinline__ void operator()(AccRef acc, const pg8::Unit& u, int wr, int wc, int, int) const {
;     ...
;                     for (int j = 0; j < 4; ++j) { v[j] = acc[ai][bj][m][0][j] * rstd; v[4 + j] = acc[ai][bj][m][1][j] * rstd; }
;                     const bool ropet = (pn == 6 || pn == 7 || (pn == 8 && bj == 0)) && ((wc & 1) == 0);
;                     if (ropet) {
;                         float pv[8];
; #pragma unroll
;                         for (int j = 0; j < 8; ++j) pv[j] = __shfl_xor(v[j], 16);
;                         if (fq < 2) {
;                             const f32x4* cs = (const f32x4*)(rope + (size_t)pos * 16);
;                             const float sg = (fq == 0) ? -1.f : 1.f;
; #pragma unroll
;                             for (int jj = 0; jj < 4; ++jj) { const f32x4 t = cs[jj];
;                                 v[2 * jj] = v[2 * jj] * t[0] + sg * pv[2 * jj] * t[1];
;                                 v[2 * jj + 1] = v[2 * jj + 1] * t[2] + sg * pv[2 * jj + 1] * t[3]; }
;                         }
.LBB0_994:
	v_mov_b32_e32 v51, v50
	v_pk_mul_f32 v[36:37], v[36:37], v[50:51]
	v_pk_mul_f32 v[32:33], v[32:33], v[50:51]
	v_pk_mul_f32 v[38:39], v[38:39], v[50:51]
	s_and_b64 vcc, exec, s[14:15]
	v_pk_mul_f32 v[34:35], v[34:35], v[50:51]
	s_cbranch_vccnz .LBB0_998
	ds_bpermute_b32 v44, v197, v36
	ds_bpermute_b32 v45, v197, v37
	ds_bpermute_b32 v42, v197, v38
	ds_bpermute_b32 v43, v197, v39
	ds_bpermute_b32 v40, v197, v32
	ds_bpermute_b32 v41, v197, v33
	ds_bpermute_b32 v47, v197, v34
	ds_bpermute_b32 v46, v197, v35
	s_and_saveexec_b64 s[30:31], s[8:9]
	s_cbranch_execz .LBB0_997
	v_subrev_u32_e32 v240, s32, v48
	ds_read_b128 v[58:61], v240 offset:48
	ds_read_b128 v[62:65], v240 offset:32
	ds_read_b128 v[66:69], v240 offset:16
	s_nop 0
	ds_read_b128 v[48:51], v240
	s_waitcnt lgkmcnt(1)
	v_mul_f32_e32 v47, v142, v47
	v_pk_mul_f32 v[44:45], v[142:143], v[44:45] op_sel_hi:[0,1]
	v_pk_mul_f32 v[42:43], v[142:143], v[42:43] op_sel_hi:[0,1]
	v_pk_mul_f32 v[40:41], v[142:143], v[40:41] op_sel_hi:[0,1]
	s_waitcnt lgkmcnt(0)
	v_mul_f32_e32 v34, v34, v58
	v_mov_b32_e32 v70, v48
	v_mov_b32_e32 v71, v50
	v_mov_b32_e32 v50, v49
	v_mov_b32_e32 v48, v66
	v_mov_b32_e32 v49, v68
	v_pk_mul_f32 v[38:39], v[38:39], v[48:49]
	v_mov_b32_e32 v48, v62
	v_mov_b32_e32 v49, v64
	v_pk_mul_f32 v[32:33], v[32:33], v[48:49]
	v_mul_f32_e32 v48, v47, v59
	s_waitcnt lgkmcnt(0)
	v_mul_f32_e32 v47, v142, v46
	v_mov_b32_e32 v46, v35
	v_pk_mul_f32 v[46:47], v[46:47], v[60:61]
	v_pk_mul_f32 v[36:37], v[36:37], v[70:71]
	v_mov_b32_e32 v68, v67
	v_mov_b32_e32 v64, v63
	v_mov_b32_e32 v35, v47
	v_mov_b32_e32 v49, v46
	v_pk_fma_f32 v[36:37], v[44:45], v[50:51], v[36:37]
	v_pk_fma_f32 v[38:39], v[42:43], v[68:69], v[38:39]
	v_pk_fma_f32 v[32:33], v[40:41], v[64:65], v[32:33]
	v_pk_add_f32 v[34:35], v[34:35], v[48:49]

;     __device__ __forceinline__ void operator()(AccRef acc, const pg8::Unit& u, int wr, int wc, int, int) const {
;     ...
;                 const float rstd = __builtin_amdgcn_rsqf(sq[ai][m] * (1.0f / DM) + EPS) * (isq ? QSCALE : 1.0f);
;                 const int pos = samp ? 2048 + ((row - MP) & 63) : (row & 16383);
; #pragma unroll
;                 for (int bj = 0; bj < 2; ++bj) {
;                     const int c0 = pn * 256 + bj * 128 + wc * 32 + 8 * fq;
;                     float v[8];
; #pragma unroll
;                     for (int j = 0; j < 4; ++j) { v[j] = acc[ai][bj][m][0][j] * rstd; v[4 + j] = acc[ai][bj][m][1][j] * rstd; }
;                     const bool ropet = (pn == 6 || pn == 7 || (pn == 8 && bj == 0)) && ((wc & 1) == 0);
;                     if (ropet) {
;                         float pv[8];
; #pragma unroll
;                         for (int j = 0; j < 8; ++j) pv[j] = __shfl_xor(v[j], 16);
;                         if (fq < 2) {
;                             const f32x4* cs = (const f32x4*)(rope + (size_t)pos * 16);
;                             const float sg = (fq == 0) ? -1.f : 1.f;
; #pragma unroll
;                             for (int jj = 0; jj < 4; ++jj) { const f32x4 t = cs[jj];
;                                 v[2 * jj] = v[2 * jj] * t[0] + sg * pv[2 * jj] * t[1];
;                                 v[2 * jj + 1] = v[2 * jj + 1] * t[2] + sg * pv[2 * jj + 1] * t[3]; }
;                         }
.LBB0_1002:
	s_nop 1
	v_fmamk_f32 v32, v155, 0x3a800000, v170
	v_rsq_f32_e32 v32, v32
	s_movk_i32 s30, 0x3fef
	v_bitop3_b32 v35, v74, s30, 32 bitop3:0xc8
	v_cndmask_b32_e64 v33, v35, v107, s[6:7]
	v_lshlrev_b32_e32 v136, 6, v33
	v_mul_f32_e32 v34, v151, v32
	v_lshl_add_u64 v[32:33], s[76:77], 0, v[136:137]
	v_pk_mul_f32 v[28:29], v[28:29], v[34:35] op_sel_hi:[1,0]
	v_pk_mul_f32 v[24:25], v[24:25], v[34:35] op_sel_hi:[1,0]
	v_pk_mul_f32 v[30:31], v[30:31], v[34:35] op_sel_hi:[1,0]
	s_and_b64 vcc, exec, s[12:13]
	v_pk_mul_f32 v[26:27], v[26:27], v[34:35] op_sel_hi:[1,0]
	s_cbranch_vccnz .LBB0_1006
	ds_bpermute_b32 v40, v197, v28
	ds_bpermute_b32 v41, v197, v29
	ds_bpermute_b32 v38, v197, v30
	ds_bpermute_b32 v39, v197, v31
	ds_bpermute_b32 v36, v197, v24
	ds_bpermute_b32 v37, v197, v25
	ds_bpermute_b32 v43, v197, v26
	ds_bpermute_b32 v42, v197, v27
	s_and_saveexec_b64 s[30:31], s[8:9]
	s_cbranch_execz .LBB0_1005
	s_waitcnt lgkmcnt(8)
	v_subrev_u32_e32 v240, s32, v32
	ds_read_b128 v[44:47], v240 offset:48
	ds_read_b128 v[48:51], v240 offset:32
	ds_read_b128 v[52:55], v240 offset:16
	ds_read_b128 v[56:59], v240
	s_waitcnt lgkmcnt(1)
	v_mul_f32_e32 v43, v142, v43
	v_pk_mul_f32 v[40:41], v[142:143], v[40:41] op_sel_hi:[0,1]
	v_pk_mul_f32 v[38:39], v[142:143], v[38:39] op_sel_hi:[0,1]
	v_pk_mul_f32 v[36:37], v[142:143], v[36:37] op_sel_hi:[0,1]
	s_waitcnt lgkmcnt(0)
	v_mul_f32_e32 v26, v26, v44
	v_mul_f32_e32 v44, v43, v45
	s_waitcnt lgkmcnt(0)
	v_mul_f32_e32 v43, v142, v42
	v_mov_b32_e32 v42, v27
	v_mov_b32_e32 v60, v56
	v_mov_b32_e32 v61, v58
	v_mov_b32_e32 v58, v57
	v_mov_b32_e32 v56, v52
	v_mov_b32_e32 v57, v54
	v_mov_b32_e32 v54, v53
	v_mov_b32_e32 v52, v48
	v_mov_b32_e32 v53, v50
	v_pk_mul_f32 v[42:43], v[42:43], v[46:47]
	v_pk_mul_f32 v[28:29], v[28:29], v[60:61]
	v_pk_mul_f32 v[30:31], v[30:31], v[56:57]
	v_pk_mul_f32 v[24:25], v[24:25], v[52:53]
	v_mov_b32_e32 v50, v49
	v_mov_b32_e32 v27, v43
	v_mov_b32_e32 v45, v42
	v_pk_fma_f32 v[28:29], v[40:41], v[58:59], v[28:29]
	v_pk_fma_f32 v[30:31], v[38:39], v[54:55], v[30:31]
	v_pk_fma_f32 v[24:25], v[36:37], v[50:51], v[24:25]
	v_pk_add_f32 v[26:27], v[26:27], v[44:45]

;     __device__ __forceinline__ void operator()(AccRef acc, const pg8::Unit& u, int wr, int wc, int, int) const {
;     ...
;                     for (int j = 0; j < 4; ++j) { v[j] = acc[ai][bj][m][0][j] * rstd; v[4 + j] = acc[ai][bj][m][1][j] * rstd; }
;                     const bool ropet = (pn == 6 || pn == 7 || (pn == 8 && bj == 0)) && ((wc & 1) == 0);
;                     if (ropet) {
;                         float pv[8];
; #pragma unroll
;                         for (int j = 0; j < 8; ++j) pv[j] = __shfl_xor(v[j], 16);
;                         if (fq < 2) {
;                             const f32x4* cs = (const f32x4*)(rope + (size_t)pos * 16);
;                             const float sg = (fq == 0) ? -1.f : 1.f;
; #pragma unroll
;                             for (int jj = 0; jj < 4; ++jj) { const f32x4 t = cs[jj];
;                                 v[2 * jj] = v[2 * jj] * t[0] + sg * pv[2 * jj] * t[1];
;                                 v[2 * jj + 1] = v[2 * jj + 1] * t[2] + sg * pv[2 * jj + 1] * t[3]; }
;                         }
.LBB0_1010:
	v_mov_b32_e32 v35, v34
	v_pk_mul_f32 v[20:21], v[20:21], v[34:35]
	v_pk_mul_f32 v[16:17], v[16:17], v[34:35]
	v_pk_mul_f32 v[22:23], v[22:23], v[34:35]
	s_and_b64 vcc, exec, s[14:15]
	v_pk_mul_f32 v[18:19], v[18:19], v[34:35]
	s_cbranch_vccnz .LBB0_1014
	ds_bpermute_b32 v28, v197, v20
	ds_bpermute_b32 v29, v197, v21
	ds_bpermute_b32 v26, v197, v22
	ds_bpermute_b32 v27, v197, v23
	ds_bpermute_b32 v24, v197, v16
	ds_bpermute_b32 v25, v197, v17
	ds_bpermute_b32 v31, v197, v18
	ds_bpermute_b32 v30, v197, v19
	s_and_saveexec_b64 s[30:31], s[8:9]
	s_cbranch_execz .LBB0_1013
	v_subrev_u32_e32 v240, s32, v32
	ds_read_b128 v[42:45], v240 offset:48
	ds_read_b128 v[46:49], v240 offset:32
	ds_read_b128 v[50:53], v240 offset:16
	s_nop 0
	ds_read_b128 v[32:35], v240
	s_waitcnt lgkmcnt(1)
	v_mul_f32_e32 v31, v142, v31
	v_pk_mul_f32 v[28:29], v[142:143], v[28:29] op_sel_hi:[0,1]
	v_pk_mul_f32 v[26:27], v[142:143], v[26:27] op_sel_hi:[0,1]
	v_pk_mul_f32 v[24:25], v[142:143], v[24:25] op_sel_hi:[0,1]
	s_waitcnt lgkmcnt(0)
	v_mul_f32_e32 v18, v18, v42
	v_mov_b32_e32 v54, v32
	v_mov_b32_e32 v55, v34
	v_mov_b32_e32 v34, v33
	v_mov_b32_e32 v32, v50
	v_mov_b32_e32 v33, v52
	v_pk_mul_f32 v[22:23], v[22:23], v[32:33]
	v_mov_b32_e32 v32, v46
	v_mov_b32_e32 v33, v48
	v_pk_mul_f32 v[16:17], v[16:17], v[32:33]
	v_mul_f32_e32 v32, v31, v43
	s_waitcnt lgkmcnt(0)
	v_mul_f32_e32 v31, v142, v30
	v_mov_b32_e32 v30, v19
	v_pk_mul_f32 v[30:31], v[30:31], v[44:45]
	v_pk_mul_f32 v[20:21], v[20:21], v[54:55]
	v_mov_b32_e32 v52, v51
	v_mov_b32_e32 v48, v47
	v_mov_b32_e32 v19, v31
	v_mov_b32_e32 v33, v30
	v_pk_fma_f32 v[20:21], v[28:29], v[34:35], v[20:21]
	v_pk_fma_f32 v[22:23], v[26:27], v[52:53], v[22:23]
	v_pk_fma_f32 v[16:17], v[24:25], v[48:49], v[16:17]
	v_pk_add_f32 v[18:19], v[18:19], v[32:33]

;     __device__ __forceinline__ void operator()(AccRef acc, const pg8::Unit& u, int wr, int wc, int, int) const {
;     ...
;                 const float rstd = __builtin_amdgcn_rsqf(sq[ai][m] * (1.0f / DM) + EPS) * (isq ? QSCALE : 1.0f);
;                 const int pos = samp ? 2048 + ((row - MP) & 63) : (row & 16383);
; #pragma unroll
;                 for (int bj = 0; bj < 2; ++bj) {
;                     const int c0 = pn * 256 + bj * 128 + wc * 32 + 8 * fq;
;                     float v[8];
; #pragma unroll
;                     for (int j = 0; j < 4; ++j) { v[j] = acc[ai][bj][m][0][j] * rstd; v[4 + j] = acc[ai][bj][m][1][j] * rstd; }
;                     const bool ropet = (pn == 6 || pn == 7 || (pn == 8 && bj == 0)) && ((wc & 1) == 0);
;                     if (ropet) {
;                         float pv[8];
; #pragma unroll
;                         for (int j = 0; j < 8; ++j) pv[j] = __shfl_xor(v[j], 16);
;                         if (fq < 2) {
;                             const f32x4* cs = (const f32x4*)(rope + (size_t)pos * 16);
;                             const float sg = (fq == 0) ? -1.f : 1.f;
; #pragma unroll
;                             for (int jj = 0; jj < 4; ++jj) { const f32x4 t = cs[jj];
;                                 v[2 * jj] = v[2 * jj] * t[0] + sg * pv[2 * jj] * t[1];
;                                 v[2 * jj + 1] = v[2 * jj + 1] * t[2] + sg * pv[2 * jj + 1] * t[3]; }
;                         }
.LBB0_1018:
	s_nop 1
	v_fmamk_f32 v16, v153, 0x3a800000, v170
	v_rsq_f32_e32 v16, v16
	s_movk_i32 s30, 0x3fff
	v_bitop3_b32 v19, v74, s30, 48 bitop3:0xc8
	v_cndmask_b32_e64 v17, v19, v91, s[6:7]
	v_lshlrev_b32_e32 v136, 6, v17
	v_mul_f32_e32 v18, v151, v16
	v_lshl_add_u64 v[16:17], s[76:77], 0, v[136:137]
	v_pk_mul_f32 v[12:13], v[12:13], v[18:19] op_sel_hi:[1,0]
	v_pk_mul_f32 v[8:9], v[8:9], v[18:19] op_sel_hi:[1,0]
	v_pk_mul_f32 v[14:15], v[14:15], v[18:19] op_sel_hi:[1,0]
	s_and_b64 vcc, exec, s[12:13]
	v_pk_mul_f32 v[10:11], v[10:11], v[18:19] op_sel_hi:[1,0]
	s_cbranch_vccnz .LBB0_1022
	ds_bpermute_b32 v24, v197, v12
	ds_bpermute_b32 v25, v197, v13
	ds_bpermute_b32 v22, v197, v14
	ds_bpermute_b32 v23, v197, v15
	ds_bpermute_b32 v20, v197, v8
	ds_bpermute_b32 v21, v197, v9
	ds_bpermute_b32 v27, v197, v10
	ds_bpermute_b32 v26, v197, v11
	s_and_saveexec_b64 s[12:13], s[8:9]
	s_cbranch_execz .LBB0_1021
	s_waitcnt lgkmcnt(8)
	v_subrev_u32_e32 v240, s32, v16
	ds_read_b128 v[28:31], v240 offset:48
	ds_read_b128 v[32:35], v240 offset:32
	ds_read_b128 v[36:39], v240 offset:16
	ds_read_b128 v[40:43], v240
	s_waitcnt lgkmcnt(1)
	v_mul_f32_e32 v27, v142, v27
	v_pk_mul_f32 v[24:25], v[142:143], v[24:25] op_sel_hi:[0,1]
	v_pk_mul_f32 v[22:23], v[142:143], v[22:23] op_sel_hi:[0,1]
	v_pk_mul_f32 v[20:21], v[142:143], v[20:21] op_sel_hi:[0,1]
	s_waitcnt lgkmcnt(0)
	v_mul_f32_e32 v10, v10, v28
	v_mul_f32_e32 v28, v27, v29
	s_waitcnt lgkmcnt(0)
	v_mul_f32_e32 v27, v142, v26
	v_mov_b32_e32 v26, v11
	v_mov_b32_e32 v44, v40
	v_mov_b32_e32 v45, v42
	v_mov_b32_e32 v42, v41
	v_mov_b32_e32 v40, v36
	v_mov_b32_e32 v41, v38
	v_mov_b32_e32 v38, v37
	v_mov_b32_e32 v36, v32
	v_mov_b32_e32 v37, v34
	v_pk_mul_f32 v[26:27], v[26:27], v[30:31]
	v_pk_mul_f32 v[12:13], v[12:13], v[44:45]
	v_pk_mul_f32 v[14:15], v[14:15], v[40:41]
	v_pk_mul_f32 v[8:9], v[8:9], v[36:37]
	v_mov_b32_e32 v34, v33
	v_mov_b32_e32 v11, v27
	v_mov_b32_e32 v29, v26
	v_pk_fma_f32 v[12:13], v[24:25], v[42:43], v[12:13]
	v_pk_fma_f32 v[14:15], v[22:23], v[38:39], v[14:15]
	v_pk_fma_f32 v[8:9], v[20:21], v[34:35], v[8:9]
	v_pk_add_f32 v[10:11], v[10:11], v[28:29]

;     __device__ __forceinline__ void operator()(AccRef acc, const pg8::Unit& u, int wr, int wc, int, int) const {
;     ...
;                     for (int j = 0; j < 4; ++j) { v[j] = acc[ai][bj][m][0][j] * rstd; v[4 + j] = acc[ai][bj][m][1][j] * rstd; }
;                     const bool ropet = (pn == 6 || pn == 7 || (pn == 8 && bj == 0)) && ((wc & 1) == 0);
;                     if (ropet) {
;                         float pv[8];
; #pragma unroll
;                         for (int j = 0; j < 8; ++j) pv[j] = __shfl_xor(v[j], 16);
;                         if (fq < 2) {
;                             const f32x4* cs = (const f32x4*)(rope + (size_t)pos * 16);
;                             const float sg = (fq == 0) ? -1.f : 1.f;
; #pragma unroll
;                             for (int jj = 0; jj < 4; ++jj) { const f32x4 t = cs[jj];
;                                 v[2 * jj] = v[2 * jj] * t[0] + sg * pv[2 * jj] * t[1];
;                                 v[2 * jj + 1] = v[2 * jj + 1] * t[2] + sg * pv[2 * jj + 1] * t[3]; }
;                         }
.LBB0_1026:
	v_mov_b32_e32 v19, v18
	v_pk_mul_f32 v[4:5], v[4:5], v[18:19]
	v_pk_mul_f32 v[0:1], v[0:1], v[18:19]
	v_pk_mul_f32 v[6:7], v[6:7], v[18:19]
	s_and_b64 vcc, exec, s[14:15]
	v_pk_mul_f32 v[2:3], v[2:3], v[18:19]
	s_cbranch_vccnz .LBB0_1030
	ds_bpermute_b32 v12, v197, v4
	ds_bpermute_b32 v13, v197, v5
	ds_bpermute_b32 v10, v197, v6
	ds_bpermute_b32 v11, v197, v7
	ds_bpermute_b32 v8, v197, v0
	ds_bpermute_b32 v9, v197, v1
	ds_bpermute_b32 v15, v197, v2
	ds_bpermute_b32 v14, v197, v3
	s_and_saveexec_b64 s[12:13], s[8:9]
	s_cbranch_execz .LBB0_1029
	v_subrev_u32_e32 v240, s32, v16
	ds_read_b128 v[26:29], v240 offset:48
	ds_read_b128 v[30:33], v240 offset:32
	ds_read_b128 v[34:37], v240 offset:16
	s_nop 0
	ds_read_b128 v[16:19], v240
	s_waitcnt lgkmcnt(1)
	v_mul_f32_e32 v15, v142, v15
	v_pk_mul_f32 v[12:13], v[142:143], v[12:13] op_sel_hi:[0,1]
	v_pk_mul_f32 v[10:11], v[142:143], v[10:11] op_sel_hi:[0,1]
	v_pk_mul_f32 v[8:9], v[142:143], v[8:9] op_sel_hi:[0,1]
	s_waitcnt lgkmcnt(0)
	v_mul_f32_e32 v2, v2, v26
	v_mov_b32_e32 v38, v16
	v_mov_b32_e32 v39, v18
	v_mov_b32_e32 v18, v17
	v_mov_b32_e32 v16, v34
	v_mov_b32_e32 v17, v36
	v_pk_mul_f32 v[6:7], v[6:7], v[16:17]
	v_mov_b32_e32 v16, v30
	v_mov_b32_e32 v17, v32
	v_pk_mul_f32 v[0:1], v[0:1], v[16:17]
	v_mul_f32_e32 v16, v15, v27
	s_waitcnt lgkmcnt(0)
	v_mul_f32_e32 v15, v142, v14
	v_mov_b32_e32 v14, v3
	v_pk_mul_f32 v[14:15], v[14:15], v[28:29]
	v_pk_mul_f32 v[4:5], v[4:5], v[38:39]
	v_mov_b32_e32 v36, v35
	v_mov_b32_e32 v32, v31
	v_mov_b32_e32 v3, v15
	v_mov_b32_e32 v17, v14
	v_pk_fma_f32 v[4:5], v[12:13], v[18:19], v[4:5]
	v_pk_fma_f32 v[6:7], v[10:11], v[36:37], v[6:7]
	v_pk_fma_f32 v[0:1], v[8:9], v[32:33], v[0:1]
	v_pk_add_f32 v[2:3], v[2:3], v[16:17]

; #define LAS __attribute__((address_space(3)))
; __global__ void __launch_bounds__(NWAVES * 64, 2) mega_fwd(Args args) {
;     extern __shared__ __attribute__((aligned(16))) unsigned char lds_raw[];
;     LAS unsigned char* lds = (LAS unsigned char*)lds_raw;
	.amdhsa_kernel _Z8mega_fwd4Args
		.amdhsa_group_segment_fixed_size 24576
		.amdhsa_private_segment_fixed_size 0
		.amdhsa_kernarg_size 440
		.amdhsa_user_sgpr_count 2
		.amdhsa_user_sgpr_dispatch_ptr 0
		.amdhsa_user_sgpr_queue_ptr 0
		.amdhsa_user_sgpr_kernarg_segment_ptr 1
		.amdhsa_user_sgpr_dispatch_id 0
		.amdhsa_user_sgpr_kernarg_preload_length 0
		.amdhsa_user_sgpr_kernarg_preload_offset 0
		.amdhsa_user_sgpr_private_segment_size 0
		.amdhsa_uses_dynamic_stack 0
		.amdhsa_enable_private_segment 0
		.amdhsa_system_sgpr_workgroup_id_x 1
		.amdhsa_system_sgpr_workgroup_id_y 0
		.amdhsa_system_sgpr_workgroup_id_z 0
		.amdhsa_system_sgpr_workgroup_info 0
		.amdhsa_system_vgpr_workitem_id 2
		.amdhsa_next_free_vgpr 250
		.amdhsa_next_free_sgpr 98
		.amdhsa_accum_offset 252
		.amdhsa_reserve_vcc 1
		.amdhsa_float_round_mode_32 0
		.amdhsa_float_round_mode_16_64 0
		.amdhsa_float_denorm_mode_32 3
		.amdhsa_float_denorm_mode_16_64 3
		.amdhsa_dx10_clamp 1
		.amdhsa_ieee_mode 1
		.amdhsa_fp16_overflow 0
		.amdhsa_tg_split 0
		.amdhsa_exception_fp_ieee_invalid_op 0
		.amdhsa_exception_fp_denorm_src 0
		.amdhsa_exception_fp_ieee_div_zero 0
		.amdhsa_exception_fp_ieee_overflow 0
		.amdhsa_exception_fp_ieee_underflow 0
		.amdhsa_exception_fp_ieee_inexact 0
		.amdhsa_exception_int_div_zero 0
	.end_amdhsa_kernel

; #define LAS __attribute__((address_space(3)))
; __global__ void __launch_bounds__(NWAVES * 64, 2) mega_fwd(Args args) {
;     extern __shared__ __attribute__((aligned(16))) unsigned char lds_raw[];
;     LAS unsigned char* lds = (LAS unsigned char*)lds_raw;
amdhsa.kernels:
  - .agpr_count:     0
    .args:
      - .offset:         0
        .size:           184
        .value_kind:     by_value
      - .offset:         184
        .size:           4
        .value_kind:     hidden_block_count_x
      - .offset:         188
        .size:           4
        .value_kind:     hidden_block_count_y
      - .offset:         192
        .size:           4
        .value_kind:     hidden_block_count_z
      - .offset:         196
        .size:           2
        .value_kind:     hidden_group_size_x
      - .offset:         198
        .size:           2
        .value_kind:     hidden_group_size_y
      - .offset:         200
        .size:           2
        .value_kind:     hidden_group_size_z
      - .offset:         202
        .size:           2
        .value_kind:     hidden_remainder_x
      - .offset:         204
        .size:           2
        .value_kind:     hidden_remainder_y
      - .offset:         206
        .size:           2
        .value_kind:     hidden_remainder_z
      - .offset:         224
        .size:           8
        .value_kind:     hidden_global_offset_x
      - .offset:         232
        .size:           8
        .value_kind:     hidden_global_offset_y
      - .offset:         240
        .size:           8
        .value_kind:     hidden_global_offset_z
      - .offset:         248
        .size:           2
        .value_kind:     hidden_grid_dims
      - .offset:         272
        .size:           8
        .value_kind:     hidden_multigrid_sync_arg
      - .offset:         304
        .size:           4
        .value_kind:     hidden_dynamic_lds_size
    .group_segment_fixed_size: 24576
    .kernarg_segment_align: 8
    .kernarg_segment_size: 440
    .language:       OpenCL C
    .language_version:
      - 2
      - 0
    .max_flat_workgroup_size: 512
    .name:           _Z8mega_fwd4Args
    .private_segment_fixed_size: 0
    .sgpr_count:     104
    .sgpr_spill_count: 70
    .symbol:         _Z8mega_fwd4Args.kd
    .uniform_work_group_size: 1
    .uses_dynamic_stack: false
    .vgpr_count:     250
    .vgpr_spill_count: 0
    .wavefront_size: 64
